# phase-1 GEMM: tile staging through LDS-DMA (global_load_lds_dwordx4, swizzle on the source addresses), no staging VGPRs and no ds_write in the k-loop
# speedup vs baseline: 1.0350x; 1.0102x over previous
.LBB0_174:
	s_or_b64 exec, exec, s[4:5]
	v_bfe_u32 v151, v100, 5, 1
	s_cmpk_gt_i32 s2, 0x98f
	v_lshrrev_b32_e32 v147, 5, v100
	v_lshlrev_b32_e32 v111, 6, v100
	v_lshlrev_b32_e32 v148, 4, v151
	v_lshlrev_b32_e32 v149, 2, v100
	s_waitcnt lgkmcnt(0)
	s_barrier
	s_cbranch_scc1 .LBB0_223
	v_and_b32_e32 v0, 0x1c0, v105
	v_or_b32_e32 v1, v0, v101
	v_lshl_or_b32 v0, v151, 2, v0
	s_movk_i32 s0, 0x90
	v_and_b32_e32 v2, 0x5f, v100
	v_mul_u32_u24_e32 v0, 0x84, v0
	v_and_b32_e32 v64, 64, v111
	v_mul_u32_u24_e32 v3, 0x90, v2
	v_mad_u32_u24 v76, v1, s0, v148
	v_mul_i32_i24_e32 v1, 0xffffff74, v2
	v_lshlrev_b32_e32 v0, 2, v0
	v_mad_u32_u24 v74, v105, s0, v64
	v_mad_u32_u24 v75, v2, s0, v148
	v_add3_u32 v77, v3, v1, v0
	s_movk_i32 s0, 0xe0
	v_and_b32_e32 v0, 0xe0, v100
	v_cmp_eq_u32_e32 vcc, s0, v0
	v_readlane_b32 s36, v238, 48
	v_add_u32_e32 v0, 0x300, v100
	v_mov_b32_e32 v65, 0
	v_readlane_b32 s37, v238, 49
	v_readlane_b32 s38, v238, 50
	v_readlane_b32 s39, v238, 51
	v_readlane_b32 s40, v238, 52
	v_readlane_b32 s41, v238, 53
	v_readlane_b32 s42, v238, 54
	v_readlane_b32 s43, v238, 55
	v_readlane_b32 s44, v238, 56
	v_readlane_b32 s45, v238, 57
	v_readlane_b32 s46, v238, 58
	v_readlane_b32 s47, v238, 59
	v_readlane_b32 s48, v238, 60
	v_readlane_b32 s49, v238, 61
	v_readlane_b32 s50, v238, 62
	v_readlane_b32 s51, v238, 63
	v_lshrrev_b32_e32 v79, 5, v0
	v_add_u32_e32 v0, 0x200, v100
	v_lshl_add_u64 v[66:67], s[44:45], 0, v[64:65]
	v_readlane_b32 s36, v238, 16
	v_lshrrev_b32_e32 v81, 5, v0
	v_add_u32_e32 v0, 0x100, v100
	v_readlane_b32 s48, v238, 28
	v_readlane_b32 s49, v238, 29
	s_movk_i32 s0, 0x210
	v_lshrrev_b32_e32 v83, 5, v0
	v_and_b32_e32 v78, 0x7c, v149
	v_lshl_add_u64 v[68:69], s[48:49], 0, v[64:65]
	v_lshrrev_b32_e32 v69, 3, v100
	v_and_b32_e32 v68, 7, v100
	v_bfe_u32 v244, v100, 4, 3
	v_xor_b32_e32 v244, v244, v68
	v_lshlrev_b32_e32 v244, 4, v244
	v_lshl_or_b32 v66, v69, 11, v244
	v_add_u32_e32 v67, 0x10000, v66
	v_add_u32_e32 v68, 0x20000, v66
	v_add_u32_e32 v69, 0x30000, v66
	v_and_b32_e32 v244, 15, v100
	v_bfe_u32 v245, v100, 4, 2
	v_bfe_u32 v246, v100, 1, 3
	v_xor_b32_e32 v247, v245, v246
	v_lshlrev_b32_e32 v247, 4, v247
	v_lshl_or_b32 v247, v244, 7, v247
	v_bfe_u32 v246, v100, 7, 1
	v_lshl_add_u32 v239, v246, 13, v247
	v_xor_b32_e32 v240, 64, v239
	v_bfe_u32 v246, v100, 6, 1
	v_lshl_add_u32 v241, v246, 13, v247
	v_add_u32_e32 v241, 0x4000, v241
	v_xor_b32_e32 v242, 64, v241
	v_bfe_u32 v247, v100, 7, 1
	v_lshlrev_b32_e32 v247, 6, v247
	v_lshl_add_u32 v247, v245, 2, v247
	v_mul_u32_u24_e32 v247, 0x84, v247
	v_lshl_add_u32 v247, v246, 6, v247
	v_add_u32_e32 v247, v247, v244
	v_lshlrev_b32_e32 v243, 2, v247
	v_mad_u32_u24 v80, v79, s0, v98
	v_mad_u32_u24 v82, v81, s0, v98
	v_mad_u32_u24 v84, v83, s0, v98
	v_mad_u32_u24 v85, v147, s0, v98
	s_movk_i32 s0, 0x1200
	s_movk_i32 s1, 0x7fff
	s_movk_i32 s3, 0x3fff
	s_movk_i32 s11, 0x700
	s_movk_i32 s62, 0x7ff
	v_add_u32_e32 v86, 0x400, v77
	v_add_u32_e32 v87, 0x1000, v77
	v_add_u32_e32 v88, 0x1400, v77
	v_add_u32_e32 v89, 0x2000, v77
	v_add_u32_e32 v90, 0x2400, v77
	v_add_u32_e32 v91, 0x3000, v77
	v_add_u32_e32 v92, 0x3200, v77
	v_add_u32_e32 v93, 0x3400, v77
	v_add_u32_e32 v94, 0x3600, v77
	v_add_u32_e32 v95, 0x4000, v77
	v_add_u32_e32 v97, 0x4400, v77
	v_add_u32_e32 v99, 0x4800, v77
	v_add_u32_e32 v103, 0x5000, v77
	v_add_u32_e32 v108, 0x5400, v77
	v_add_u32_e32 v109, 0x5800, v77
	v_add_u32_e32 v110, 0x6000, v77
	v_add_u32_e32 v112, 0x6400, v77
	v_add_u32_e32 v113, 0x6800, v77
	v_add_u32_e32 v114, 0x7200, v77
	v_add_u32_e32 v115, 0x7400, v77
	v_add_u32_e32 v116, 0x7600, v77
	v_add_u32_e32 v117, 0x7800, v77
	v_mov_b32_e32 v118, 1
	s_mov_b32 s63, s2
	v_readlane_b32 s37, v238, 17
	v_readlane_b32 s38, v238, 18
	v_readlane_b32 s39, v238, 19
	v_readlane_b32 s40, v238, 20
	v_readlane_b32 s41, v238, 21
	v_readlane_b32 s42, v238, 22
	v_readlane_b32 s43, v238, 23
	v_readlane_b32 s44, v238, 24
	v_readlane_b32 s45, v238, 25
	v_readlane_b32 s46, v238, 26
	v_readlane_b32 s47, v238, 27
	v_readlane_b32 s50, v238, 30
	v_readlane_b32 s51, v238, 31
	s_branch .LBB0_177

.LBB0_177:
	s_mul_hi_i32 s4, s63, 0x38e38e39
	s_lshr_b32 s5, s4, 31
	s_ashr_i32 s4, s4, 2
	s_add_i32 s4, s4, s5
	s_mul_i32 s5, s4, 18
	s_sub_i32 s5, s63, s5
	s_lshl_b32 s6, s4, 7
	s_lshl_b32 s4, s5, 7
	v_readlane_b32 s98, v238, 56
	v_readlane_b32 s99, v238, 57
	v_readlane_b32 s100, v238, 28
	v_readlane_b32 s101, v238, 29
	s_lshl_b32 s5, s6, 11
	s_nop 0
	s_add_u32 s98, s98, s5
	s_addc_u32 s99, s99, 0
	s_lshl_b32 s5, s4, 11
	s_add_u32 s100, s100, s5
	s_addc_u32 s101, s101, 0
	v_lshrrev_b32_e32 v244, 6, v100
	v_lshlrev_b32_e32 v244, 10, v244
	s_nop 1
	v_readfirstlane_b32 s5, v244
	s_nop 3
	s_add_u32 m0, s5, 0x0
	s_nop 0
	global_load_lds_dwordx4 v66, s[98:99]
	s_add_u32 m0, s5, 0x1000
	s_nop 0
	global_load_lds_dwordx4 v67, s[98:99]
	s_add_u32 m0, s5, 0x2000
	s_nop 0
	global_load_lds_dwordx4 v68, s[98:99]
	s_add_u32 m0, s5, 0x3000
	s_nop 0
	global_load_lds_dwordx4 v69, s[98:99]
	s_add_u32 m0, s5, 0x4000
	s_nop 0
	global_load_lds_dwordx4 v66, s[100:101]
	s_add_u32 m0, s5, 0x5000
	s_nop 0
	global_load_lds_dwordx4 v67, s[100:101]
	s_add_u32 m0, s5, 0x6000
	s_nop 0
	global_load_lds_dwordx4 v68, s[100:101]
	s_add_u32 m0, s5, 0x7000
	s_nop 0
	global_load_lds_dwordx4 v69, s[100:101]
	v_readlane_b32 s12, v238, 32
	v_readlane_b32 s36, v238, 16
	v_readlane_b32 s13, v238, 33
	v_readlane_b32 s14, v238, 34
	v_readlane_b32 s38, v238, 18
	v_readlane_b32 s39, v238, 19
	s_mov_b32 s14, 0
	v_readlane_b32 s15, v238, 35
	v_readlane_b32 s16, v238, 36
	v_readlane_b32 s17, v238, 37
	v_readlane_b32 s18, v238, 38
	v_readlane_b32 s19, v238, 39
	v_readlane_b32 s20, v238, 40
	v_readlane_b32 s21, v238, 41
	v_readlane_b32 s22, v238, 42
	v_readlane_b32 s23, v238, 43
	v_readlane_b32 s24, v238, 44
	v_readlane_b32 s25, v238, 45
	v_readlane_b32 s26, v238, 46
	v_readlane_b32 s27, v238, 47
	v_readlane_b32 s37, v238, 17
	v_readlane_b32 s40, v238, 20
	v_readlane_b32 s41, v238, 21
	v_readlane_b32 s42, v238, 22
	v_readlane_b32 s43, v238, 23
	v_readlane_b32 s44, v238, 24
	v_readlane_b32 s45, v238, 25
	v_readlane_b32 s46, v238, 26
	v_readlane_b32 s47, v238, 27
	v_readlane_b32 s48, v238, 28
	v_readlane_b32 s49, v238, 29
	v_readlane_b32 s50, v238, 30
	v_readlane_b32 s51, v238, 31
	s_waitcnt vmcnt(0)
	s_barrier
	s_add_u32 s98, s98, 0x80
	s_addc_u32 s99, s99, 0
	s_add_u32 s100, s100, 0x80
	s_addc_u32 s101, s101, 0
	ds_read_b128 v[120:123], v239
	ds_read_b128 v[140:143], v241
	ds_read_b128 v[152:155], v241 offset:2048
	ds_read_b128 v[156:159], v241 offset:4096
	ds_read_b128 v[160:163], v241 offset:6144
	ds_read_b128 v[124:127], v239 offset:2048
	ds_read_b128 v[128:131], v239 offset:4096
	ds_read_b128 v[132:135], v239 offset:6144
	s_waitcnt lgkmcnt(6)
	v_mfma_f32_16x16x32_bf16 v[0:3], v[120:123], v[140:143], 0
	ds_read_b128 v[164:167], v240
	s_waitcnt lgkmcnt(6)
	v_mfma_f32_16x16x32_bf16 v[4:7], v[120:123], v[152:155], 0
	ds_read_b128 v[86:89], v242
	s_waitcnt lgkmcnt(6)
	v_mfma_f32_16x16x32_bf16 v[8:11], v[120:123], v[156:159], 0
	ds_read_b128 v[90:93], v242 offset:2048
	s_waitcnt lgkmcnt(6)
	v_mfma_f32_16x16x32_bf16 v[12:15], v[120:123], v[160:163], 0
	ds_read_b128 v[112:115], v242 offset:4096
	s_waitcnt lgkmcnt(6)
	v_mfma_f32_16x16x32_bf16 v[16:19], v[124:127], v[140:143], 0
	ds_read_b128 v[252:255], v242 offset:6144
	v_mfma_f32_16x16x32_bf16 v[20:23], v[124:127], v[152:155], 0
	ds_read_b128 v[168:171], v240 offset:2048
	v_mfma_f32_16x16x32_bf16 v[24:27], v[124:127], v[156:159], 0
	ds_read_b128 v[244:247], v240 offset:4096
	v_mfma_f32_16x16x32_bf16 v[28:31], v[124:127], v[160:163], 0
	ds_read_b128 v[248:251], v240 offset:6144
	s_add_u32 m0, s5, 0x8000
	s_waitcnt lgkmcnt(9)
	v_mfma_f32_16x16x32_bf16 v[32:35], v[128:131], v[140:143], 0
	global_load_lds_dwordx4 v66, s[98:99]
	s_add_u32 m0, s5, 0x9000
	v_mfma_f32_16x16x32_bf16 v[36:39], v[128:131], v[152:155], 0
	global_load_lds_dwordx4 v67, s[98:99]
	s_add_u32 m0, s5, 0xa000
	v_mfma_f32_16x16x32_bf16 v[40:43], v[128:131], v[156:159], 0
	global_load_lds_dwordx4 v68, s[98:99]
	s_add_u32 m0, s5, 0xb000
	v_mfma_f32_16x16x32_bf16 v[44:47], v[128:131], v[160:163], 0
	global_load_lds_dwordx4 v69, s[98:99]
	s_add_u32 m0, s5, 0xc000
	s_waitcnt lgkmcnt(8)
	v_mfma_f32_16x16x32_bf16 v[48:51], v[132:135], v[140:143], 0
	global_load_lds_dwordx4 v66, s[100:101]
	s_add_u32 m0, s5, 0xd000
	v_mfma_f32_16x16x32_bf16 v[52:55], v[132:135], v[152:155], 0
	global_load_lds_dwordx4 v67, s[100:101]
	s_add_u32 m0, s5, 0xe000
	v_mfma_f32_16x16x32_bf16 v[56:59], v[132:135], v[156:159], 0
	global_load_lds_dwordx4 v68, s[100:101]
	s_add_u32 m0, s5, 0xf000
	v_mfma_f32_16x16x32_bf16 v[60:63], v[132:135], v[160:163], 0
	global_load_lds_dwordx4 v69, s[100:101]
	s_waitcnt lgkmcnt(6)
	v_mfma_f32_16x16x32_bf16 v[0:3], v[164:167], v[86:89], v[0:3]
	s_waitcnt lgkmcnt(5)
	v_mfma_f32_16x16x32_bf16 v[4:7], v[164:167], v[90:93], v[4:7]
	s_waitcnt lgkmcnt(4)
	v_mfma_f32_16x16x32_bf16 v[8:11], v[164:167], v[112:115], v[8:11]
	s_waitcnt lgkmcnt(3)
	v_mfma_f32_16x16x32_bf16 v[12:15], v[164:167], v[252:255], v[12:15]
	s_waitcnt lgkmcnt(2)
	v_mfma_f32_16x16x32_bf16 v[16:19], v[168:171], v[86:89], v[16:19]
	v_mfma_f32_16x16x32_bf16 v[20:23], v[168:171], v[90:93], v[20:23]
	v_mfma_f32_16x16x32_bf16 v[24:27], v[168:171], v[112:115], v[24:27]
	v_mfma_f32_16x16x32_bf16 v[28:31], v[168:171], v[252:255], v[28:31]
	s_waitcnt lgkmcnt(1)
	v_mfma_f32_16x16x32_bf16 v[32:35], v[244:247], v[86:89], v[32:35]
	v_mfma_f32_16x16x32_bf16 v[36:39], v[244:247], v[90:93], v[36:39]
	v_mfma_f32_16x16x32_bf16 v[40:43], v[244:247], v[112:115], v[40:43]
	v_mfma_f32_16x16x32_bf16 v[44:47], v[244:247], v[252:255], v[44:47]
	s_waitcnt lgkmcnt(0)
	v_mfma_f32_16x16x32_bf16 v[48:51], v[248:251], v[86:89], v[48:51]
	v_mfma_f32_16x16x32_bf16 v[52:55], v[248:251], v[90:93], v[52:55]
	v_mfma_f32_16x16x32_bf16 v[56:59], v[248:251], v[112:115], v[56:59]
	v_mfma_f32_16x16x32_bf16 v[60:63], v[248:251], v[252:255], v[60:63]
	s_waitcnt vmcnt(0) lgkmcnt(0)
	s_barrier
	s_add_u32 s98, s98, 0x80
	s_addc_u32 s99, s99, 0
	s_add_u32 s100, s100, 0x80
	s_addc_u32 s101, s101, 0
	ds_read_b128 v[120:123], v239 offset:32768
	ds_read_b128 v[140:143], v241 offset:32768
	ds_read_b128 v[152:155], v241 offset:34816
	ds_read_b128 v[156:159], v241 offset:36864
	ds_read_b128 v[160:163], v241 offset:38912
	ds_read_b128 v[124:127], v239 offset:34816
	ds_read_b128 v[128:131], v239 offset:36864
	ds_read_b128 v[132:135], v239 offset:38912
	s_waitcnt lgkmcnt(6)
	v_mfma_f32_16x16x32_bf16 v[0:3], v[120:123], v[140:143], v[0:3]
	ds_read_b128 v[164:167], v240 offset:32768
	s_waitcnt lgkmcnt(6)
	v_mfma_f32_16x16x32_bf16 v[4:7], v[120:123], v[152:155], v[4:7]
	ds_read_b128 v[86:89], v242 offset:32768
	s_waitcnt lgkmcnt(6)
	v_mfma_f32_16x16x32_bf16 v[8:11], v[120:123], v[156:159], v[8:11]
	ds_read_b128 v[90:93], v242 offset:34816
	s_waitcnt lgkmcnt(6)
	v_mfma_f32_16x16x32_bf16 v[12:15], v[120:123], v[160:163], v[12:15]
	ds_read_b128 v[112:115], v242 offset:36864
	s_waitcnt lgkmcnt(6)
	v_mfma_f32_16x16x32_bf16 v[16:19], v[124:127], v[140:143], v[16:19]
	ds_read_b128 v[252:255], v242 offset:38912
	v_mfma_f32_16x16x32_bf16 v[20:23], v[124:127], v[152:155], v[20:23]
	ds_read_b128 v[168:171], v240 offset:34816
	v_mfma_f32_16x16x32_bf16 v[24:27], v[124:127], v[156:159], v[24:27]
	ds_read_b128 v[244:247], v240 offset:36864
	v_mfma_f32_16x16x32_bf16 v[28:31], v[124:127], v[160:163], v[28:31]
	ds_read_b128 v[248:251], v240 offset:38912
	s_add_u32 m0, s5, 0x0
	s_waitcnt lgkmcnt(9)
	v_mfma_f32_16x16x32_bf16 v[32:35], v[128:131], v[140:143], v[32:35]
	global_load_lds_dwordx4 v66, s[98:99]
	s_add_u32 m0, s5, 0x1000
	v_mfma_f32_16x16x32_bf16 v[36:39], v[128:131], v[152:155], v[36:39]
	global_load_lds_dwordx4 v67, s[98:99]
	s_add_u32 m0, s5, 0x2000
	v_mfma_f32_16x16x32_bf16 v[40:43], v[128:131], v[156:159], v[40:43]
	global_load_lds_dwordx4 v68, s[98:99]
	s_add_u32 m0, s5, 0x3000
	v_mfma_f32_16x16x32_bf16 v[44:47], v[128:131], v[160:163], v[44:47]
	global_load_lds_dwordx4 v69, s[98:99]
	s_add_u32 m0, s5, 0x4000
	s_waitcnt lgkmcnt(8)
	v_mfma_f32_16x16x32_bf16 v[48:51], v[132:135], v[140:143], v[48:51]
	global_load_lds_dwordx4 v66, s[100:101]
	s_add_u32 m0, s5, 0x5000
	v_mfma_f32_16x16x32_bf16 v[52:55], v[132:135], v[152:155], v[52:55]
	global_load_lds_dwordx4 v67, s[100:101]
	s_add_u32 m0, s5, 0x6000
	v_mfma_f32_16x16x32_bf16 v[56:59], v[132:135], v[156:159], v[56:59]
	global_load_lds_dwordx4 v68, s[100:101]
	s_add_u32 m0, s5, 0x7000
	v_mfma_f32_16x16x32_bf16 v[60:63], v[132:135], v[160:163], v[60:63]
	global_load_lds_dwordx4 v69, s[100:101]
	s_waitcnt lgkmcnt(6)
	v_mfma_f32_16x16x32_bf16 v[0:3], v[164:167], v[86:89], v[0:3]
	s_waitcnt lgkmcnt(5)
	v_mfma_f32_16x16x32_bf16 v[4:7], v[164:167], v[90:93], v[4:7]
	s_waitcnt lgkmcnt(4)
	v_mfma_f32_16x16x32_bf16 v[8:11], v[164:167], v[112:115], v[8:11]
	s_waitcnt lgkmcnt(3)
	v_mfma_f32_16x16x32_bf16 v[12:15], v[164:167], v[252:255], v[12:15]
	s_waitcnt lgkmcnt(2)
	v_mfma_f32_16x16x32_bf16 v[16:19], v[168:171], v[86:89], v[16:19]
	v_mfma_f32_16x16x32_bf16 v[20:23], v[168:171], v[90:93], v[20:23]
	v_mfma_f32_16x16x32_bf16 v[24:27], v[168:171], v[112:115], v[24:27]
	v_mfma_f32_16x16x32_bf16 v[28:31], v[168:171], v[252:255], v[28:31]
	s_waitcnt lgkmcnt(1)
	v_mfma_f32_16x16x32_bf16 v[32:35], v[244:247], v[86:89], v[32:35]
	v_mfma_f32_16x16x32_bf16 v[36:39], v[244:247], v[90:93], v[36:39]
	v_mfma_f32_16x16x32_bf16 v[40:43], v[244:247], v[112:115], v[40:43]
	v_mfma_f32_16x16x32_bf16 v[44:47], v[244:247], v[252:255], v[44:47]
	s_waitcnt lgkmcnt(0)
	v_mfma_f32_16x16x32_bf16 v[48:51], v[248:251], v[86:89], v[48:51]
	v_mfma_f32_16x16x32_bf16 v[52:55], v[248:251], v[90:93], v[52:55]
	v_mfma_f32_16x16x32_bf16 v[56:59], v[248:251], v[112:115], v[56:59]
	v_mfma_f32_16x16x32_bf16 v[60:63], v[248:251], v[252:255], v[60:63]
	s_waitcnt vmcnt(0) lgkmcnt(0)
	s_barrier
	s_add_u32 s98, s98, 0x80
	s_addc_u32 s99, s99, 0
	s_add_u32 s100, s100, 0x80
	s_addc_u32 s101, s101, 0
	ds_read_b128 v[120:123], v239
	ds_read_b128 v[140:143], v241
	ds_read_b128 v[152:155], v241 offset:2048
	ds_read_b128 v[156:159], v241 offset:4096
	ds_read_b128 v[160:163], v241 offset:6144
	ds_read_b128 v[124:127], v239 offset:2048
	ds_read_b128 v[128:131], v239 offset:4096
	ds_read_b128 v[132:135], v239 offset:6144
	s_waitcnt lgkmcnt(6)
	v_mfma_f32_16x16x32_bf16 v[0:3], v[120:123], v[140:143], v[0:3]
	ds_read_b128 v[164:167], v240
	s_waitcnt lgkmcnt(6)
	v_mfma_f32_16x16x32_bf16 v[4:7], v[120:123], v[152:155], v[4:7]
	ds_read_b128 v[86:89], v242
	s_waitcnt lgkmcnt(6)
	v_mfma_f32_16x16x32_bf16 v[8:11], v[120:123], v[156:159], v[8:11]
	ds_read_b128 v[90:93], v242 offset:2048
	s_waitcnt lgkmcnt(6)
	v_mfma_f32_16x16x32_bf16 v[12:15], v[120:123], v[160:163], v[12:15]
	ds_read_b128 v[112:115], v242 offset:4096
	s_waitcnt lgkmcnt(6)
	v_mfma_f32_16x16x32_bf16 v[16:19], v[124:127], v[140:143], v[16:19]
	ds_read_b128 v[252:255], v242 offset:6144
	v_mfma_f32_16x16x32_bf16 v[20:23], v[124:127], v[152:155], v[20:23]
	ds_read_b128 v[168:171], v240 offset:2048
	v_mfma_f32_16x16x32_bf16 v[24:27], v[124:127], v[156:159], v[24:27]
	ds_read_b128 v[244:247], v240 offset:4096
	v_mfma_f32_16x16x32_bf16 v[28:31], v[124:127], v[160:163], v[28:31]
	ds_read_b128 v[248:251], v240 offset:6144
	s_add_u32 m0, s5, 0x8000
	s_waitcnt lgkmcnt(9)
	v_mfma_f32_16x16x32_bf16 v[32:35], v[128:131], v[140:143], v[32:35]
	global_load_lds_dwordx4 v66, s[98:99]
	s_add_u32 m0, s5, 0x9000
	v_mfma_f32_16x16x32_bf16 v[36:39], v[128:131], v[152:155], v[36:39]
	global_load_lds_dwordx4 v67, s[98:99]
	s_add_u32 m0, s5, 0xa000
	v_mfma_f32_16x16x32_bf16 v[40:43], v[128:131], v[156:159], v[40:43]
	global_load_lds_dwordx4 v68, s[98:99]
	s_add_u32 m0, s5, 0xb000
	v_mfma_f32_16x16x32_bf16 v[44:47], v[128:131], v[160:163], v[44:47]
	global_load_lds_dwordx4 v69, s[98:99]
	s_add_u32 m0, s5, 0xc000
	s_waitcnt lgkmcnt(8)
	v_mfma_f32_16x16x32_bf16 v[48:51], v[132:135], v[140:143], v[48:51]
	global_load_lds_dwordx4 v66, s[100:101]
	s_add_u32 m0, s5, 0xd000
	v_mfma_f32_16x16x32_bf16 v[52:55], v[132:135], v[152:155], v[52:55]
	global_load_lds_dwordx4 v67, s[100:101]
	s_add_u32 m0, s5, 0xe000
	v_mfma_f32_16x16x32_bf16 v[56:59], v[132:135], v[156:159], v[56:59]
	global_load_lds_dwordx4 v68, s[100:101]
	s_add_u32 m0, s5, 0xf000
	v_mfma_f32_16x16x32_bf16 v[60:63], v[132:135], v[160:163], v[60:63]
	global_load_lds_dwordx4 v69, s[100:101]
	s_waitcnt lgkmcnt(6)
	v_mfma_f32_16x16x32_bf16 v[0:3], v[164:167], v[86:89], v[0:3]
	s_waitcnt lgkmcnt(5)
	v_mfma_f32_16x16x32_bf16 v[4:7], v[164:167], v[90:93], v[4:7]
	s_waitcnt lgkmcnt(4)
	v_mfma_f32_16x16x32_bf16 v[8:11], v[164:167], v[112:115], v[8:11]
	s_waitcnt lgkmcnt(3)
	v_mfma_f32_16x16x32_bf16 v[12:15], v[164:167], v[252:255], v[12:15]
	s_waitcnt lgkmcnt(2)
	v_mfma_f32_16x16x32_bf16 v[16:19], v[168:171], v[86:89], v[16:19]
	v_mfma_f32_16x16x32_bf16 v[20:23], v[168:171], v[90:93], v[20:23]
	v_mfma_f32_16x16x32_bf16 v[24:27], v[168:171], v[112:115], v[24:27]
	v_mfma_f32_16x16x32_bf16 v[28:31], v[168:171], v[252:255], v[28:31]
	s_waitcnt lgkmcnt(1)
	v_mfma_f32_16x16x32_bf16 v[32:35], v[244:247], v[86:89], v[32:35]
	v_mfma_f32_16x16x32_bf16 v[36:39], v[244:247], v[90:93], v[36:39]
	v_mfma_f32_16x16x32_bf16 v[40:43], v[244:247], v[112:115], v[40:43]
	v_mfma_f32_16x16x32_bf16 v[44:47], v[244:247], v[252:255], v[44:47]
	s_waitcnt lgkmcnt(0)
	v_mfma_f32_16x16x32_bf16 v[48:51], v[248:251], v[86:89], v[48:51]
	v_mfma_f32_16x16x32_bf16 v[52:55], v[248:251], v[90:93], v[52:55]
	v_mfma_f32_16x16x32_bf16 v[56:59], v[248:251], v[112:115], v[56:59]
	v_mfma_f32_16x16x32_bf16 v[60:63], v[248:251], v[252:255], v[60:63]
	s_waitcnt vmcnt(0) lgkmcnt(0)
	s_barrier
	s_add_u32 s98, s98, 0x80
	s_addc_u32 s99, s99, 0
	s_add_u32 s100, s100, 0x80
	s_addc_u32 s101, s101, 0
	ds_read_b128 v[120:123], v239 offset:32768
	ds_read_b128 v[140:143], v241 offset:32768
	ds_read_b128 v[152:155], v241 offset:34816
	ds_read_b128 v[156:159], v241 offset:36864
	ds_read_b128 v[160:163], v241 offset:38912
	ds_read_b128 v[124:127], v239 offset:34816
	ds_read_b128 v[128:131], v239 offset:36864
	ds_read_b128 v[132:135], v239 offset:38912
	s_waitcnt lgkmcnt(6)
	v_mfma_f32_16x16x32_bf16 v[0:3], v[120:123], v[140:143], v[0:3]
	ds_read_b128 v[164:167], v240 offset:32768
	s_waitcnt lgkmcnt(6)
	v_mfma_f32_16x16x32_bf16 v[4:7], v[120:123], v[152:155], v[4:7]
	ds_read_b128 v[86:89], v242 offset:32768
	s_waitcnt lgkmcnt(6)
	v_mfma_f32_16x16x32_bf16 v[8:11], v[120:123], v[156:159], v[8:11]
	ds_read_b128 v[90:93], v242 offset:34816
	s_waitcnt lgkmcnt(6)
	v_mfma_f32_16x16x32_bf16 v[12:15], v[120:123], v[160:163], v[12:15]
	ds_read_b128 v[112:115], v242 offset:36864
	s_waitcnt lgkmcnt(6)
	v_mfma_f32_16x16x32_bf16 v[16:19], v[124:127], v[140:143], v[16:19]
	ds_read_b128 v[252:255], v242 offset:38912
	v_mfma_f32_16x16x32_bf16 v[20:23], v[124:127], v[152:155], v[20:23]
	ds_read_b128 v[168:171], v240 offset:34816
	v_mfma_f32_16x16x32_bf16 v[24:27], v[124:127], v[156:159], v[24:27]
	ds_read_b128 v[244:247], v240 offset:36864
	v_mfma_f32_16x16x32_bf16 v[28:31], v[124:127], v[160:163], v[28:31]
	ds_read_b128 v[248:251], v240 offset:38912
	s_add_u32 m0, s5, 0x0
	s_waitcnt lgkmcnt(9)
	v_mfma_f32_16x16x32_bf16 v[32:35], v[128:131], v[140:143], v[32:35]
	global_load_lds_dwordx4 v66, s[98:99]
	s_add_u32 m0, s5, 0x1000
	v_mfma_f32_16x16x32_bf16 v[36:39], v[128:131], v[152:155], v[36:39]
	global_load_lds_dwordx4 v67, s[98:99]
	s_add_u32 m0, s5, 0x2000
	v_mfma_f32_16x16x32_bf16 v[40:43], v[128:131], v[156:159], v[40:43]
	global_load_lds_dwordx4 v68, s[98:99]
	s_add_u32 m0, s5, 0x3000
	v_mfma_f32_16x16x32_bf16 v[44:47], v[128:131], v[160:163], v[44:47]
	global_load_lds_dwordx4 v69, s[98:99]
	s_add_u32 m0, s5, 0x4000
	s_waitcnt lgkmcnt(8)
	v_mfma_f32_16x16x32_bf16 v[48:51], v[132:135], v[140:143], v[48:51]
	global_load_lds_dwordx4 v66, s[100:101]
	s_add_u32 m0, s5, 0x5000
	v_mfma_f32_16x16x32_bf16 v[52:55], v[132:135], v[152:155], v[52:55]
	global_load_lds_dwordx4 v67, s[100:101]
	s_add_u32 m0, s5, 0x6000
	v_mfma_f32_16x16x32_bf16 v[56:59], v[132:135], v[156:159], v[56:59]
	global_load_lds_dwordx4 v68, s[100:101]
	s_add_u32 m0, s5, 0x7000
	v_mfma_f32_16x16x32_bf16 v[60:63], v[132:135], v[160:163], v[60:63]
	global_load_lds_dwordx4 v69, s[100:101]
	s_waitcnt lgkmcnt(6)
	v_mfma_f32_16x16x32_bf16 v[0:3], v[164:167], v[86:89], v[0:3]
	s_waitcnt lgkmcnt(5)
	v_mfma_f32_16x16x32_bf16 v[4:7], v[164:167], v[90:93], v[4:7]
	s_waitcnt lgkmcnt(4)
	v_mfma_f32_16x16x32_bf16 v[8:11], v[164:167], v[112:115], v[8:11]
	s_waitcnt lgkmcnt(3)
	v_mfma_f32_16x16x32_bf16 v[12:15], v[164:167], v[252:255], v[12:15]
	s_waitcnt lgkmcnt(2)
	v_mfma_f32_16x16x32_bf16 v[16:19], v[168:171], v[86:89], v[16:19]
	v_mfma_f32_16x16x32_bf16 v[20:23], v[168:171], v[90:93], v[20:23]
	v_mfma_f32_16x16x32_bf16 v[24:27], v[168:171], v[112:115], v[24:27]
	v_mfma_f32_16x16x32_bf16 v[28:31], v[168:171], v[252:255], v[28:31]
	s_waitcnt lgkmcnt(1)
	v_mfma_f32_16x16x32_bf16 v[32:35], v[244:247], v[86:89], v[32:35]
	v_mfma_f32_16x16x32_bf16 v[36:39], v[244:247], v[90:93], v[36:39]
	v_mfma_f32_16x16x32_bf16 v[40:43], v[244:247], v[112:115], v[40:43]
	v_mfma_f32_16x16x32_bf16 v[44:47], v[244:247], v[252:255], v[44:47]
	s_waitcnt lgkmcnt(0)
	v_mfma_f32_16x16x32_bf16 v[48:51], v[248:251], v[86:89], v[48:51]
	v_mfma_f32_16x16x32_bf16 v[52:55], v[248:251], v[90:93], v[52:55]
	v_mfma_f32_16x16x32_bf16 v[56:59], v[248:251], v[112:115], v[56:59]
	v_mfma_f32_16x16x32_bf16 v[60:63], v[248:251], v[252:255], v[60:63]
	s_waitcnt vmcnt(0) lgkmcnt(0)
	s_barrier
	s_add_u32 s98, s98, 0x80
	s_addc_u32 s99, s99, 0
	s_add_u32 s100, s100, 0x80
	s_addc_u32 s101, s101, 0
	ds_read_b128 v[120:123], v239
	ds_read_b128 v[140:143], v241
	ds_read_b128 v[152:155], v241 offset:2048
	ds_read_b128 v[156:159], v241 offset:4096
	ds_read_b128 v[160:163], v241 offset:6144
	ds_read_b128 v[124:127], v239 offset:2048
	ds_read_b128 v[128:131], v239 offset:4096
	ds_read_b128 v[132:135], v239 offset:6144
	s_waitcnt lgkmcnt(6)
	v_mfma_f32_16x16x32_bf16 v[0:3], v[120:123], v[140:143], v[0:3]
	ds_read_b128 v[164:167], v240
	s_waitcnt lgkmcnt(6)
	v_mfma_f32_16x16x32_bf16 v[4:7], v[120:123], v[152:155], v[4:7]
	ds_read_b128 v[86:89], v242
	s_waitcnt lgkmcnt(6)
	v_mfma_f32_16x16x32_bf16 v[8:11], v[120:123], v[156:159], v[8:11]
	ds_read_b128 v[90:93], v242 offset:2048
	s_waitcnt lgkmcnt(6)
	v_mfma_f32_16x16x32_bf16 v[12:15], v[120:123], v[160:163], v[12:15]
	ds_read_b128 v[112:115], v242 offset:4096
	s_waitcnt lgkmcnt(6)
	v_mfma_f32_16x16x32_bf16 v[16:19], v[124:127], v[140:143], v[16:19]
	ds_read_b128 v[252:255], v242 offset:6144
	v_mfma_f32_16x16x32_bf16 v[20:23], v[124:127], v[152:155], v[20:23]
	ds_read_b128 v[168:171], v240 offset:2048
	v_mfma_f32_16x16x32_bf16 v[24:27], v[124:127], v[156:159], v[24:27]
	ds_read_b128 v[244:247], v240 offset:4096
	v_mfma_f32_16x16x32_bf16 v[28:31], v[124:127], v[160:163], v[28:31]
	ds_read_b128 v[248:251], v240 offset:6144
	s_add_u32 m0, s5, 0x8000
	s_waitcnt lgkmcnt(9)
	v_mfma_f32_16x16x32_bf16 v[32:35], v[128:131], v[140:143], v[32:35]
	global_load_lds_dwordx4 v66, s[98:99]
	s_add_u32 m0, s5, 0x9000
	v_mfma_f32_16x16x32_bf16 v[36:39], v[128:131], v[152:155], v[36:39]
	global_load_lds_dwordx4 v67, s[98:99]
	s_add_u32 m0, s5, 0xa000
	v_mfma_f32_16x16x32_bf16 v[40:43], v[128:131], v[156:159], v[40:43]
	global_load_lds_dwordx4 v68, s[98:99]
	s_add_u32 m0, s5, 0xb000
	v_mfma_f32_16x16x32_bf16 v[44:47], v[128:131], v[160:163], v[44:47]
	global_load_lds_dwordx4 v69, s[98:99]
	s_add_u32 m0, s5, 0xc000
	s_waitcnt lgkmcnt(8)
	v_mfma_f32_16x16x32_bf16 v[48:51], v[132:135], v[140:143], v[48:51]
	global_load_lds_dwordx4 v66, s[100:101]
	s_add_u32 m0, s5, 0xd000
	v_mfma_f32_16x16x32_bf16 v[52:55], v[132:135], v[152:155], v[52:55]
	global_load_lds_dwordx4 v67, s[100:101]
	s_add_u32 m0, s5, 0xe000
	v_mfma_f32_16x16x32_bf16 v[56:59], v[132:135], v[156:159], v[56:59]
	global_load_lds_dwordx4 v68, s[100:101]
	s_add_u32 m0, s5, 0xf000
	v_mfma_f32_16x16x32_bf16 v[60:63], v[132:135], v[160:163], v[60:63]
	global_load_lds_dwordx4 v69, s[100:101]
	s_waitcnt lgkmcnt(6)
	v_mfma_f32_16x16x32_bf16 v[0:3], v[164:167], v[86:89], v[0:3]
	s_waitcnt lgkmcnt(5)
	v_mfma_f32_16x16x32_bf16 v[4:7], v[164:167], v[90:93], v[4:7]
	s_waitcnt lgkmcnt(4)
	v_mfma_f32_16x16x32_bf16 v[8:11], v[164:167], v[112:115], v[8:11]
	s_waitcnt lgkmcnt(3)
	v_mfma_f32_16x16x32_bf16 v[12:15], v[164:167], v[252:255], v[12:15]
	s_waitcnt lgkmcnt(2)
	v_mfma_f32_16x16x32_bf16 v[16:19], v[168:171], v[86:89], v[16:19]
	v_mfma_f32_16x16x32_bf16 v[20:23], v[168:171], v[90:93], v[20:23]
	v_mfma_f32_16x16x32_bf16 v[24:27], v[168:171], v[112:115], v[24:27]
	v_mfma_f32_16x16x32_bf16 v[28:31], v[168:171], v[252:255], v[28:31]
	s_waitcnt lgkmcnt(1)
	v_mfma_f32_16x16x32_bf16 v[32:35], v[244:247], v[86:89], v[32:35]
	v_mfma_f32_16x16x32_bf16 v[36:39], v[244:247], v[90:93], v[36:39]
	v_mfma_f32_16x16x32_bf16 v[40:43], v[244:247], v[112:115], v[40:43]
	v_mfma_f32_16x16x32_bf16 v[44:47], v[244:247], v[252:255], v[44:47]
	s_waitcnt lgkmcnt(0)
	v_mfma_f32_16x16x32_bf16 v[48:51], v[248:251], v[86:89], v[48:51]
	v_mfma_f32_16x16x32_bf16 v[52:55], v[248:251], v[90:93], v[52:55]
	v_mfma_f32_16x16x32_bf16 v[56:59], v[248:251], v[112:115], v[56:59]
	v_mfma_f32_16x16x32_bf16 v[60:63], v[248:251], v[252:255], v[60:63]
	s_waitcnt vmcnt(0) lgkmcnt(0)
	s_barrier
	s_add_u32 s98, s98, 0x80
	s_addc_u32 s99, s99, 0
	s_add_u32 s100, s100, 0x80
	s_addc_u32 s101, s101, 0
	ds_read_b128 v[120:123], v239 offset:32768
	ds_read_b128 v[140:143], v241 offset:32768
	ds_read_b128 v[152:155], v241 offset:34816
	ds_read_b128 v[156:159], v241 offset:36864
	ds_read_b128 v[160:163], v241 offset:38912
	ds_read_b128 v[124:127], v239 offset:34816
	ds_read_b128 v[128:131], v239 offset:36864
	ds_read_b128 v[132:135], v239 offset:38912
	s_waitcnt lgkmcnt(6)
	v_mfma_f32_16x16x32_bf16 v[0:3], v[120:123], v[140:143], v[0:3]
	ds_read_b128 v[164:167], v240 offset:32768
	s_waitcnt lgkmcnt(6)
	v_mfma_f32_16x16x32_bf16 v[4:7], v[120:123], v[152:155], v[4:7]
	ds_read_b128 v[86:89], v242 offset:32768
	s_waitcnt lgkmcnt(6)
	v_mfma_f32_16x16x32_bf16 v[8:11], v[120:123], v[156:159], v[8:11]
	ds_read_b128 v[90:93], v242 offset:34816
	s_waitcnt lgkmcnt(6)
	v_mfma_f32_16x16x32_bf16 v[12:15], v[120:123], v[160:163], v[12:15]
	ds_read_b128 v[112:115], v242 offset:36864
	s_waitcnt lgkmcnt(6)
	v_mfma_f32_16x16x32_bf16 v[16:19], v[124:127], v[140:143], v[16:19]
	ds_read_b128 v[252:255], v242 offset:38912
	v_mfma_f32_16x16x32_bf16 v[20:23], v[124:127], v[152:155], v[20:23]
	ds_read_b128 v[168:171], v240 offset:34816
	v_mfma_f32_16x16x32_bf16 v[24:27], v[124:127], v[156:159], v[24:27]
	ds_read_b128 v[244:247], v240 offset:36864
	v_mfma_f32_16x16x32_bf16 v[28:31], v[124:127], v[160:163], v[28:31]
	ds_read_b128 v[248:251], v240 offset:38912
	s_add_u32 m0, s5, 0x0
	s_waitcnt lgkmcnt(9)
	v_mfma_f32_16x16x32_bf16 v[32:35], v[128:131], v[140:143], v[32:35]
	global_load_lds_dwordx4 v66, s[98:99]
	s_add_u32 m0, s5, 0x1000
	v_mfma_f32_16x16x32_bf16 v[36:39], v[128:131], v[152:155], v[36:39]
	global_load_lds_dwordx4 v67, s[98:99]
	s_add_u32 m0, s5, 0x2000
	v_mfma_f32_16x16x32_bf16 v[40:43], v[128:131], v[156:159], v[40:43]
	global_load_lds_dwordx4 v68, s[98:99]
	s_add_u32 m0, s5, 0x3000
	v_mfma_f32_16x16x32_bf16 v[44:47], v[128:131], v[160:163], v[44:47]
	global_load_lds_dwordx4 v69, s[98:99]
	s_add_u32 m0, s5, 0x4000
	s_waitcnt lgkmcnt(8)
	v_mfma_f32_16x16x32_bf16 v[48:51], v[132:135], v[140:143], v[48:51]
	global_load_lds_dwordx4 v66, s[100:101]
	s_add_u32 m0, s5, 0x5000
	v_mfma_f32_16x16x32_bf16 v[52:55], v[132:135], v[152:155], v[52:55]
	global_load_lds_dwordx4 v67, s[100:101]
	s_add_u32 m0, s5, 0x6000
	v_mfma_f32_16x16x32_bf16 v[56:59], v[132:135], v[156:159], v[56:59]
	global_load_lds_dwordx4 v68, s[100:101]
	s_add_u32 m0, s5, 0x7000
	v_mfma_f32_16x16x32_bf16 v[60:63], v[132:135], v[160:163], v[60:63]
	global_load_lds_dwordx4 v69, s[100:101]
	s_waitcnt lgkmcnt(6)
	v_mfma_f32_16x16x32_bf16 v[0:3], v[164:167], v[86:89], v[0:3]
	s_waitcnt lgkmcnt(5)
	v_mfma_f32_16x16x32_bf16 v[4:7], v[164:167], v[90:93], v[4:7]
	s_waitcnt lgkmcnt(4)
	v_mfma_f32_16x16x32_bf16 v[8:11], v[164:167], v[112:115], v[8:11]
	s_waitcnt lgkmcnt(3)
	v_mfma_f32_16x16x32_bf16 v[12:15], v[164:167], v[252:255], v[12:15]
	s_waitcnt lgkmcnt(2)
	v_mfma_f32_16x16x32_bf16 v[16:19], v[168:171], v[86:89], v[16:19]
	v_mfma_f32_16x16x32_bf16 v[20:23], v[168:171], v[90:93], v[20:23]
	v_mfma_f32_16x16x32_bf16 v[24:27], v[168:171], v[112:115], v[24:27]
	v_mfma_f32_16x16x32_bf16 v[28:31], v[168:171], v[252:255], v[28:31]
	s_waitcnt lgkmcnt(1)
	v_mfma_f32_16x16x32_bf16 v[32:35], v[244:247], v[86:89], v[32:35]
	v_mfma_f32_16x16x32_bf16 v[36:39], v[244:247], v[90:93], v[36:39]
	v_mfma_f32_16x16x32_bf16 v[40:43], v[244:247], v[112:115], v[40:43]
	v_mfma_f32_16x16x32_bf16 v[44:47], v[244:247], v[252:255], v[44:47]
	s_waitcnt lgkmcnt(0)
	v_mfma_f32_16x16x32_bf16 v[48:51], v[248:251], v[86:89], v[48:51]
	v_mfma_f32_16x16x32_bf16 v[52:55], v[248:251], v[90:93], v[52:55]
	v_mfma_f32_16x16x32_bf16 v[56:59], v[248:251], v[112:115], v[56:59]
	v_mfma_f32_16x16x32_bf16 v[60:63], v[248:251], v[252:255], v[60:63]
	s_waitcnt vmcnt(0) lgkmcnt(0)
	s_barrier
	s_add_u32 s98, s98, 0x80
	s_addc_u32 s99, s99, 0
	s_add_u32 s100, s100, 0x80
	s_addc_u32 s101, s101, 0
	ds_read_b128 v[120:123], v239
	ds_read_b128 v[140:143], v241
	ds_read_b128 v[152:155], v241 offset:2048
	ds_read_b128 v[156:159], v241 offset:4096
	ds_read_b128 v[160:163], v241 offset:6144
	ds_read_b128 v[124:127], v239 offset:2048
	ds_read_b128 v[128:131], v239 offset:4096
	ds_read_b128 v[132:135], v239 offset:6144
	s_waitcnt lgkmcnt(6)
	v_mfma_f32_16x16x32_bf16 v[0:3], v[120:123], v[140:143], v[0:3]
	ds_read_b128 v[164:167], v240
	s_waitcnt lgkmcnt(6)
	v_mfma_f32_16x16x32_bf16 v[4:7], v[120:123], v[152:155], v[4:7]
	ds_read_b128 v[86:89], v242
	s_waitcnt lgkmcnt(6)
	v_mfma_f32_16x16x32_bf16 v[8:11], v[120:123], v[156:159], v[8:11]
	ds_read_b128 v[90:93], v242 offset:2048
	s_waitcnt lgkmcnt(6)
	v_mfma_f32_16x16x32_bf16 v[12:15], v[120:123], v[160:163], v[12:15]
	ds_read_b128 v[112:115], v242 offset:4096
	s_waitcnt lgkmcnt(6)
	v_mfma_f32_16x16x32_bf16 v[16:19], v[124:127], v[140:143], v[16:19]
	ds_read_b128 v[252:255], v242 offset:6144
	v_mfma_f32_16x16x32_bf16 v[20:23], v[124:127], v[152:155], v[20:23]
	ds_read_b128 v[168:171], v240 offset:2048
	v_mfma_f32_16x16x32_bf16 v[24:27], v[124:127], v[156:159], v[24:27]
	ds_read_b128 v[244:247], v240 offset:4096
	v_mfma_f32_16x16x32_bf16 v[28:31], v[124:127], v[160:163], v[28:31]
	ds_read_b128 v[248:251], v240 offset:6144
	s_add_u32 m0, s5, 0x8000
	s_waitcnt lgkmcnt(9)
	v_mfma_f32_16x16x32_bf16 v[32:35], v[128:131], v[140:143], v[32:35]
	global_load_lds_dwordx4 v66, s[98:99]
	s_add_u32 m0, s5, 0x9000
	v_mfma_f32_16x16x32_bf16 v[36:39], v[128:131], v[152:155], v[36:39]
	global_load_lds_dwordx4 v67, s[98:99]
	s_add_u32 m0, s5, 0xa000
	v_mfma_f32_16x16x32_bf16 v[40:43], v[128:131], v[156:159], v[40:43]
	global_load_lds_dwordx4 v68, s[98:99]
	s_add_u32 m0, s5, 0xb000
	v_mfma_f32_16x16x32_bf16 v[44:47], v[128:131], v[160:163], v[44:47]
	global_load_lds_dwordx4 v69, s[98:99]
	s_add_u32 m0, s5, 0xc000
	s_waitcnt lgkmcnt(8)
	v_mfma_f32_16x16x32_bf16 v[48:51], v[132:135], v[140:143], v[48:51]
	global_load_lds_dwordx4 v66, s[100:101]
	s_add_u32 m0, s5, 0xd000
	v_mfma_f32_16x16x32_bf16 v[52:55], v[132:135], v[152:155], v[52:55]
	global_load_lds_dwordx4 v67, s[100:101]
	s_add_u32 m0, s5, 0xe000
	v_mfma_f32_16x16x32_bf16 v[56:59], v[132:135], v[156:159], v[56:59]
	global_load_lds_dwordx4 v68, s[100:101]
	s_add_u32 m0, s5, 0xf000
	v_mfma_f32_16x16x32_bf16 v[60:63], v[132:135], v[160:163], v[60:63]
	global_load_lds_dwordx4 v69, s[100:101]
	s_waitcnt lgkmcnt(6)
	v_mfma_f32_16x16x32_bf16 v[0:3], v[164:167], v[86:89], v[0:3]
	s_waitcnt lgkmcnt(5)
	v_mfma_f32_16x16x32_bf16 v[4:7], v[164:167], v[90:93], v[4:7]
	s_waitcnt lgkmcnt(4)
	v_mfma_f32_16x16x32_bf16 v[8:11], v[164:167], v[112:115], v[8:11]
	s_waitcnt lgkmcnt(3)
	v_mfma_f32_16x16x32_bf16 v[12:15], v[164:167], v[252:255], v[12:15]
	s_waitcnt lgkmcnt(2)
	v_mfma_f32_16x16x32_bf16 v[16:19], v[168:171], v[86:89], v[16:19]
	v_mfma_f32_16x16x32_bf16 v[20:23], v[168:171], v[90:93], v[20:23]
	v_mfma_f32_16x16x32_bf16 v[24:27], v[168:171], v[112:115], v[24:27]
	v_mfma_f32_16x16x32_bf16 v[28:31], v[168:171], v[252:255], v[28:31]
	s_waitcnt lgkmcnt(1)
	v_mfma_f32_16x16x32_bf16 v[32:35], v[244:247], v[86:89], v[32:35]
	v_mfma_f32_16x16x32_bf16 v[36:39], v[244:247], v[90:93], v[36:39]
	v_mfma_f32_16x16x32_bf16 v[40:43], v[244:247], v[112:115], v[40:43]
	v_mfma_f32_16x16x32_bf16 v[44:47], v[244:247], v[252:255], v[44:47]
	s_waitcnt lgkmcnt(0)
	v_mfma_f32_16x16x32_bf16 v[48:51], v[248:251], v[86:89], v[48:51]
	v_mfma_f32_16x16x32_bf16 v[52:55], v[248:251], v[90:93], v[52:55]
	v_mfma_f32_16x16x32_bf16 v[56:59], v[248:251], v[112:115], v[56:59]
	v_mfma_f32_16x16x32_bf16 v[60:63], v[248:251], v[252:255], v[60:63]
	s_waitcnt vmcnt(0) lgkmcnt(0)
	s_barrier
	s_add_u32 s98, s98, 0x80
	s_addc_u32 s99, s99, 0
	s_add_u32 s100, s100, 0x80
	s_addc_u32 s101, s101, 0
	ds_read_b128 v[120:123], v239 offset:32768
	ds_read_b128 v[140:143], v241 offset:32768
	ds_read_b128 v[152:155], v241 offset:34816
	ds_read_b128 v[156:159], v241 offset:36864
	ds_read_b128 v[160:163], v241 offset:38912
	ds_read_b128 v[124:127], v239 offset:34816
	ds_read_b128 v[128:131], v239 offset:36864
	ds_read_b128 v[132:135], v239 offset:38912
	s_waitcnt lgkmcnt(6)
	v_mfma_f32_16x16x32_bf16 v[0:3], v[120:123], v[140:143], v[0:3]
	ds_read_b128 v[164:167], v240 offset:32768
	s_waitcnt lgkmcnt(6)
	v_mfma_f32_16x16x32_bf16 v[4:7], v[120:123], v[152:155], v[4:7]
	ds_read_b128 v[86:89], v242 offset:32768
	s_waitcnt lgkmcnt(6)
	v_mfma_f32_16x16x32_bf16 v[8:11], v[120:123], v[156:159], v[8:11]
	ds_read_b128 v[90:93], v242 offset:34816
	s_waitcnt lgkmcnt(6)
	v_mfma_f32_16x16x32_bf16 v[12:15], v[120:123], v[160:163], v[12:15]
	ds_read_b128 v[112:115], v242 offset:36864
	s_waitcnt lgkmcnt(6)
	v_mfma_f32_16x16x32_bf16 v[16:19], v[124:127], v[140:143], v[16:19]
	ds_read_b128 v[252:255], v242 offset:38912
	v_mfma_f32_16x16x32_bf16 v[20:23], v[124:127], v[152:155], v[20:23]
	ds_read_b128 v[168:171], v240 offset:34816
	v_mfma_f32_16x16x32_bf16 v[24:27], v[124:127], v[156:159], v[24:27]
	ds_read_b128 v[244:247], v240 offset:36864
	v_mfma_f32_16x16x32_bf16 v[28:31], v[124:127], v[160:163], v[28:31]
	ds_read_b128 v[248:251], v240 offset:38912
	s_add_u32 m0, s5, 0x0
	s_waitcnt lgkmcnt(9)
	v_mfma_f32_16x16x32_bf16 v[32:35], v[128:131], v[140:143], v[32:35]
	global_load_lds_dwordx4 v66, s[98:99]
	s_add_u32 m0, s5, 0x1000
	v_mfma_f32_16x16x32_bf16 v[36:39], v[128:131], v[152:155], v[36:39]
	global_load_lds_dwordx4 v67, s[98:99]
	s_add_u32 m0, s5, 0x2000
	v_mfma_f32_16x16x32_bf16 v[40:43], v[128:131], v[156:159], v[40:43]
	global_load_lds_dwordx4 v68, s[98:99]
	s_add_u32 m0, s5, 0x3000
	v_mfma_f32_16x16x32_bf16 v[44:47], v[128:131], v[160:163], v[44:47]
	global_load_lds_dwordx4 v69, s[98:99]
	s_add_u32 m0, s5, 0x4000
	s_waitcnt lgkmcnt(8)
	v_mfma_f32_16x16x32_bf16 v[48:51], v[132:135], v[140:143], v[48:51]
	global_load_lds_dwordx4 v66, s[100:101]
	s_add_u32 m0, s5, 0x5000
	v_mfma_f32_16x16x32_bf16 v[52:55], v[132:135], v[152:155], v[52:55]
	global_load_lds_dwordx4 v67, s[100:101]
	s_add_u32 m0, s5, 0x6000
	v_mfma_f32_16x16x32_bf16 v[56:59], v[132:135], v[156:159], v[56:59]
	global_load_lds_dwordx4 v68, s[100:101]
	s_add_u32 m0, s5, 0x7000
	v_mfma_f32_16x16x32_bf16 v[60:63], v[132:135], v[160:163], v[60:63]
	global_load_lds_dwordx4 v69, s[100:101]
	s_waitcnt lgkmcnt(6)
	v_mfma_f32_16x16x32_bf16 v[0:3], v[164:167], v[86:89], v[0:3]
	s_waitcnt lgkmcnt(5)
	v_mfma_f32_16x16x32_bf16 v[4:7], v[164:167], v[90:93], v[4:7]
	s_waitcnt lgkmcnt(4)
	v_mfma_f32_16x16x32_bf16 v[8:11], v[164:167], v[112:115], v[8:11]
	s_waitcnt lgkmcnt(3)
	v_mfma_f32_16x16x32_bf16 v[12:15], v[164:167], v[252:255], v[12:15]
	s_waitcnt lgkmcnt(2)
	v_mfma_f32_16x16x32_bf16 v[16:19], v[168:171], v[86:89], v[16:19]
	v_mfma_f32_16x16x32_bf16 v[20:23], v[168:171], v[90:93], v[20:23]
	v_mfma_f32_16x16x32_bf16 v[24:27], v[168:171], v[112:115], v[24:27]
	v_mfma_f32_16x16x32_bf16 v[28:31], v[168:171], v[252:255], v[28:31]
	s_waitcnt lgkmcnt(1)
	v_mfma_f32_16x16x32_bf16 v[32:35], v[244:247], v[86:89], v[32:35]
	v_mfma_f32_16x16x32_bf16 v[36:39], v[244:247], v[90:93], v[36:39]
	v_mfma_f32_16x16x32_bf16 v[40:43], v[244:247], v[112:115], v[40:43]
	v_mfma_f32_16x16x32_bf16 v[44:47], v[244:247], v[252:255], v[44:47]
	s_waitcnt lgkmcnt(0)
	v_mfma_f32_16x16x32_bf16 v[48:51], v[248:251], v[86:89], v[48:51]
	v_mfma_f32_16x16x32_bf16 v[52:55], v[248:251], v[90:93], v[52:55]
	v_mfma_f32_16x16x32_bf16 v[56:59], v[248:251], v[112:115], v[56:59]
	v_mfma_f32_16x16x32_bf16 v[60:63], v[248:251], v[252:255], v[60:63]
	s_waitcnt vmcnt(0) lgkmcnt(0)
	s_barrier
	s_add_u32 s98, s98, 0x80
	s_addc_u32 s99, s99, 0
	s_add_u32 s100, s100, 0x80
	s_addc_u32 s101, s101, 0
	ds_read_b128 v[120:123], v239
	ds_read_b128 v[140:143], v241
	ds_read_b128 v[152:155], v241 offset:2048
	ds_read_b128 v[156:159], v241 offset:4096
	ds_read_b128 v[160:163], v241 offset:6144
	ds_read_b128 v[124:127], v239 offset:2048
	ds_read_b128 v[128:131], v239 offset:4096
	ds_read_b128 v[132:135], v239 offset:6144
	s_waitcnt lgkmcnt(6)
	v_mfma_f32_16x16x32_bf16 v[0:3], v[120:123], v[140:143], v[0:3]
	ds_read_b128 v[164:167], v240
	s_waitcnt lgkmcnt(6)
	v_mfma_f32_16x16x32_bf16 v[4:7], v[120:123], v[152:155], v[4:7]
	ds_read_b128 v[86:89], v242
	s_waitcnt lgkmcnt(6)
	v_mfma_f32_16x16x32_bf16 v[8:11], v[120:123], v[156:159], v[8:11]
	ds_read_b128 v[90:93], v242 offset:2048
	s_waitcnt lgkmcnt(6)
	v_mfma_f32_16x16x32_bf16 v[12:15], v[120:123], v[160:163], v[12:15]
	ds_read_b128 v[112:115], v242 offset:4096
	s_waitcnt lgkmcnt(6)
	v_mfma_f32_16x16x32_bf16 v[16:19], v[124:127], v[140:143], v[16:19]
	ds_read_b128 v[252:255], v242 offset:6144
	v_mfma_f32_16x16x32_bf16 v[20:23], v[124:127], v[152:155], v[20:23]
	ds_read_b128 v[168:171], v240 offset:2048
	v_mfma_f32_16x16x32_bf16 v[24:27], v[124:127], v[156:159], v[24:27]
	ds_read_b128 v[244:247], v240 offset:4096
	v_mfma_f32_16x16x32_bf16 v[28:31], v[124:127], v[160:163], v[28:31]
	ds_read_b128 v[248:251], v240 offset:6144
	s_add_u32 m0, s5, 0x8000
	s_waitcnt lgkmcnt(9)
	v_mfma_f32_16x16x32_bf16 v[32:35], v[128:131], v[140:143], v[32:35]
	global_load_lds_dwordx4 v66, s[98:99]
	s_add_u32 m0, s5, 0x9000
	v_mfma_f32_16x16x32_bf16 v[36:39], v[128:131], v[152:155], v[36:39]
	global_load_lds_dwordx4 v67, s[98:99]
	s_add_u32 m0, s5, 0xa000
	v_mfma_f32_16x16x32_bf16 v[40:43], v[128:131], v[156:159], v[40:43]
	global_load_lds_dwordx4 v68, s[98:99]
	s_add_u32 m0, s5, 0xb000
	v_mfma_f32_16x16x32_bf16 v[44:47], v[128:131], v[160:163], v[44:47]
	global_load_lds_dwordx4 v69, s[98:99]
	s_add_u32 m0, s5, 0xc000
	s_waitcnt lgkmcnt(8)
	v_mfma_f32_16x16x32_bf16 v[48:51], v[132:135], v[140:143], v[48:51]
	global_load_lds_dwordx4 v66, s[100:101]
	s_add_u32 m0, s5, 0xd000
	v_mfma_f32_16x16x32_bf16 v[52:55], v[132:135], v[152:155], v[52:55]
	global_load_lds_dwordx4 v67, s[100:101]
	s_add_u32 m0, s5, 0xe000
	v_mfma_f32_16x16x32_bf16 v[56:59], v[132:135], v[156:159], v[56:59]
	global_load_lds_dwordx4 v68, s[100:101]
	s_add_u32 m0, s5, 0xf000
	v_mfma_f32_16x16x32_bf16 v[60:63], v[132:135], v[160:163], v[60:63]
	global_load_lds_dwordx4 v69, s[100:101]
	s_waitcnt lgkmcnt(6)
	v_mfma_f32_16x16x32_bf16 v[0:3], v[164:167], v[86:89], v[0:3]
	s_waitcnt lgkmcnt(5)
	v_mfma_f32_16x16x32_bf16 v[4:7], v[164:167], v[90:93], v[4:7]
	s_waitcnt lgkmcnt(4)
	v_mfma_f32_16x16x32_bf16 v[8:11], v[164:167], v[112:115], v[8:11]
	s_waitcnt lgkmcnt(3)
	v_mfma_f32_16x16x32_bf16 v[12:15], v[164:167], v[252:255], v[12:15]
	s_waitcnt lgkmcnt(2)
	v_mfma_f32_16x16x32_bf16 v[16:19], v[168:171], v[86:89], v[16:19]
	v_mfma_f32_16x16x32_bf16 v[20:23], v[168:171], v[90:93], v[20:23]
	v_mfma_f32_16x16x32_bf16 v[24:27], v[168:171], v[112:115], v[24:27]
	v_mfma_f32_16x16x32_bf16 v[28:31], v[168:171], v[252:255], v[28:31]
	s_waitcnt lgkmcnt(1)
	v_mfma_f32_16x16x32_bf16 v[32:35], v[244:247], v[86:89], v[32:35]
	v_mfma_f32_16x16x32_bf16 v[36:39], v[244:247], v[90:93], v[36:39]
	v_mfma_f32_16x16x32_bf16 v[40:43], v[244:247], v[112:115], v[40:43]
	v_mfma_f32_16x16x32_bf16 v[44:47], v[244:247], v[252:255], v[44:47]
	s_waitcnt lgkmcnt(0)
	v_mfma_f32_16x16x32_bf16 v[48:51], v[248:251], v[86:89], v[48:51]
	v_mfma_f32_16x16x32_bf16 v[52:55], v[248:251], v[90:93], v[52:55]
	v_mfma_f32_16x16x32_bf16 v[56:59], v[248:251], v[112:115], v[56:59]
	v_mfma_f32_16x16x32_bf16 v[60:63], v[248:251], v[252:255], v[60:63]
	s_waitcnt vmcnt(0) lgkmcnt(0)
	s_barrier
	s_add_u32 s98, s98, 0x80
	s_addc_u32 s99, s99, 0
	s_add_u32 s100, s100, 0x80
	s_addc_u32 s101, s101, 0
	ds_read_b128 v[120:123], v239 offset:32768
	ds_read_b128 v[140:143], v241 offset:32768
	ds_read_b128 v[152:155], v241 offset:34816
	ds_read_b128 v[156:159], v241 offset:36864
	ds_read_b128 v[160:163], v241 offset:38912
	ds_read_b128 v[124:127], v239 offset:34816
	ds_read_b128 v[128:131], v239 offset:36864
	ds_read_b128 v[132:135], v239 offset:38912
	s_waitcnt lgkmcnt(6)
	v_mfma_f32_16x16x32_bf16 v[0:3], v[120:123], v[140:143], v[0:3]
	ds_read_b128 v[164:167], v240 offset:32768
	s_waitcnt lgkmcnt(6)
	v_mfma_f32_16x16x32_bf16 v[4:7], v[120:123], v[152:155], v[4:7]
	ds_read_b128 v[86:89], v242 offset:32768
	s_waitcnt lgkmcnt(6)
	v_mfma_f32_16x16x32_bf16 v[8:11], v[120:123], v[156:159], v[8:11]
	ds_read_b128 v[90:93], v242 offset:34816
	s_waitcnt lgkmcnt(6)
	v_mfma_f32_16x16x32_bf16 v[12:15], v[120:123], v[160:163], v[12:15]
	ds_read_b128 v[112:115], v242 offset:36864
	s_waitcnt lgkmcnt(6)
	v_mfma_f32_16x16x32_bf16 v[16:19], v[124:127], v[140:143], v[16:19]
	ds_read_b128 v[252:255], v242 offset:38912
	v_mfma_f32_16x16x32_bf16 v[20:23], v[124:127], v[152:155], v[20:23]
	ds_read_b128 v[168:171], v240 offset:34816
	v_mfma_f32_16x16x32_bf16 v[24:27], v[124:127], v[156:159], v[24:27]
	ds_read_b128 v[244:247], v240 offset:36864
	v_mfma_f32_16x16x32_bf16 v[28:31], v[124:127], v[160:163], v[28:31]
	ds_read_b128 v[248:251], v240 offset:38912
	s_add_u32 m0, s5, 0x0
	s_waitcnt lgkmcnt(9)
	v_mfma_f32_16x16x32_bf16 v[32:35], v[128:131], v[140:143], v[32:35]
	global_load_lds_dwordx4 v66, s[98:99]
	s_add_u32 m0, s5, 0x1000
	v_mfma_f32_16x16x32_bf16 v[36:39], v[128:131], v[152:155], v[36:39]
	global_load_lds_dwordx4 v67, s[98:99]
	s_add_u32 m0, s5, 0x2000
	v_mfma_f32_16x16x32_bf16 v[40:43], v[128:131], v[156:159], v[40:43]
	global_load_lds_dwordx4 v68, s[98:99]
	s_add_u32 m0, s5, 0x3000
	v_mfma_f32_16x16x32_bf16 v[44:47], v[128:131], v[160:163], v[44:47]
	global_load_lds_dwordx4 v69, s[98:99]
	s_add_u32 m0, s5, 0x4000
	s_waitcnt lgkmcnt(8)
	v_mfma_f32_16x16x32_bf16 v[48:51], v[132:135], v[140:143], v[48:51]
	global_load_lds_dwordx4 v66, s[100:101]
	s_add_u32 m0, s5, 0x5000
	v_mfma_f32_16x16x32_bf16 v[52:55], v[132:135], v[152:155], v[52:55]
	global_load_lds_dwordx4 v67, s[100:101]
	s_add_u32 m0, s5, 0x6000
	v_mfma_f32_16x16x32_bf16 v[56:59], v[132:135], v[156:159], v[56:59]
	global_load_lds_dwordx4 v68, s[100:101]
	s_add_u32 m0, s5, 0x7000
	v_mfma_f32_16x16x32_bf16 v[60:63], v[132:135], v[160:163], v[60:63]
	global_load_lds_dwordx4 v69, s[100:101]
	s_waitcnt lgkmcnt(6)
	v_mfma_f32_16x16x32_bf16 v[0:3], v[164:167], v[86:89], v[0:3]
	s_waitcnt lgkmcnt(5)
	v_mfma_f32_16x16x32_bf16 v[4:7], v[164:167], v[90:93], v[4:7]
	s_waitcnt lgkmcnt(4)
	v_mfma_f32_16x16x32_bf16 v[8:11], v[164:167], v[112:115], v[8:11]
	s_waitcnt lgkmcnt(3)
	v_mfma_f32_16x16x32_bf16 v[12:15], v[164:167], v[252:255], v[12:15]
	s_waitcnt lgkmcnt(2)
	v_mfma_f32_16x16x32_bf16 v[16:19], v[168:171], v[86:89], v[16:19]
	v_mfma_f32_16x16x32_bf16 v[20:23], v[168:171], v[90:93], v[20:23]
	v_mfma_f32_16x16x32_bf16 v[24:27], v[168:171], v[112:115], v[24:27]
	v_mfma_f32_16x16x32_bf16 v[28:31], v[168:171], v[252:255], v[28:31]
	s_waitcnt lgkmcnt(1)
	v_mfma_f32_16x16x32_bf16 v[32:35], v[244:247], v[86:89], v[32:35]
	v_mfma_f32_16x16x32_bf16 v[36:39], v[244:247], v[90:93], v[36:39]
	v_mfma_f32_16x16x32_bf16 v[40:43], v[244:247], v[112:115], v[40:43]
	v_mfma_f32_16x16x32_bf16 v[44:47], v[244:247], v[252:255], v[44:47]
	s_waitcnt lgkmcnt(0)
	v_mfma_f32_16x16x32_bf16 v[48:51], v[248:251], v[86:89], v[48:51]
	v_mfma_f32_16x16x32_bf16 v[52:55], v[248:251], v[90:93], v[52:55]
	v_mfma_f32_16x16x32_bf16 v[56:59], v[248:251], v[112:115], v[56:59]
	v_mfma_f32_16x16x32_bf16 v[60:63], v[248:251], v[252:255], v[60:63]
	s_waitcnt vmcnt(0) lgkmcnt(0)
	s_barrier
	s_add_u32 s98, s98, 0x80
	s_addc_u32 s99, s99, 0
	s_add_u32 s100, s100, 0x80
	s_addc_u32 s101, s101, 0
	ds_read_b128 v[120:123], v239
	ds_read_b128 v[140:143], v241
	ds_read_b128 v[152:155], v241 offset:2048
	ds_read_b128 v[156:159], v241 offset:4096
	ds_read_b128 v[160:163], v241 offset:6144
	ds_read_b128 v[124:127], v239 offset:2048
	ds_read_b128 v[128:131], v239 offset:4096
	ds_read_b128 v[132:135], v239 offset:6144
	s_waitcnt lgkmcnt(6)
	v_mfma_f32_16x16x32_bf16 v[0:3], v[120:123], v[140:143], v[0:3]
	ds_read_b128 v[164:167], v240
	s_waitcnt lgkmcnt(6)
	v_mfma_f32_16x16x32_bf16 v[4:7], v[120:123], v[152:155], v[4:7]
	ds_read_b128 v[86:89], v242
	s_waitcnt lgkmcnt(6)
	v_mfma_f32_16x16x32_bf16 v[8:11], v[120:123], v[156:159], v[8:11]
	ds_read_b128 v[90:93], v242 offset:2048
	s_waitcnt lgkmcnt(6)
	v_mfma_f32_16x16x32_bf16 v[12:15], v[120:123], v[160:163], v[12:15]
	ds_read_b128 v[112:115], v242 offset:4096
	s_waitcnt lgkmcnt(6)
	v_mfma_f32_16x16x32_bf16 v[16:19], v[124:127], v[140:143], v[16:19]
	ds_read_b128 v[252:255], v242 offset:6144
	v_mfma_f32_16x16x32_bf16 v[20:23], v[124:127], v[152:155], v[20:23]
	ds_read_b128 v[168:171], v240 offset:2048
	v_mfma_f32_16x16x32_bf16 v[24:27], v[124:127], v[156:159], v[24:27]
	ds_read_b128 v[244:247], v240 offset:4096
	v_mfma_f32_16x16x32_bf16 v[28:31], v[124:127], v[160:163], v[28:31]
	ds_read_b128 v[248:251], v240 offset:6144
	s_add_u32 m0, s5, 0x8000
	s_waitcnt lgkmcnt(9)
	v_mfma_f32_16x16x32_bf16 v[32:35], v[128:131], v[140:143], v[32:35]
	global_load_lds_dwordx4 v66, s[98:99]
	s_add_u32 m0, s5, 0x9000
	v_mfma_f32_16x16x32_bf16 v[36:39], v[128:131], v[152:155], v[36:39]
	global_load_lds_dwordx4 v67, s[98:99]
	s_add_u32 m0, s5, 0xa000
	v_mfma_f32_16x16x32_bf16 v[40:43], v[128:131], v[156:159], v[40:43]
	global_load_lds_dwordx4 v68, s[98:99]
	s_add_u32 m0, s5, 0xb000
	v_mfma_f32_16x16x32_bf16 v[44:47], v[128:131], v[160:163], v[44:47]
	global_load_lds_dwordx4 v69, s[98:99]
	s_add_u32 m0, s5, 0xc000
	s_waitcnt lgkmcnt(8)
	v_mfma_f32_16x16x32_bf16 v[48:51], v[132:135], v[140:143], v[48:51]
	global_load_lds_dwordx4 v66, s[100:101]
	s_add_u32 m0, s5, 0xd000
	v_mfma_f32_16x16x32_bf16 v[52:55], v[132:135], v[152:155], v[52:55]
	global_load_lds_dwordx4 v67, s[100:101]
	s_add_u32 m0, s5, 0xe000
	v_mfma_f32_16x16x32_bf16 v[56:59], v[132:135], v[156:159], v[56:59]
	global_load_lds_dwordx4 v68, s[100:101]
	s_add_u32 m0, s5, 0xf000
	v_mfma_f32_16x16x32_bf16 v[60:63], v[132:135], v[160:163], v[60:63]
	global_load_lds_dwordx4 v69, s[100:101]
	s_waitcnt lgkmcnt(6)
	v_mfma_f32_16x16x32_bf16 v[0:3], v[164:167], v[86:89], v[0:3]
	s_waitcnt lgkmcnt(5)
	v_mfma_f32_16x16x32_bf16 v[4:7], v[164:167], v[90:93], v[4:7]
	s_waitcnt lgkmcnt(4)
	v_mfma_f32_16x16x32_bf16 v[8:11], v[164:167], v[112:115], v[8:11]
	s_waitcnt lgkmcnt(3)
	v_mfma_f32_16x16x32_bf16 v[12:15], v[164:167], v[252:255], v[12:15]
	s_waitcnt lgkmcnt(2)
	v_mfma_f32_16x16x32_bf16 v[16:19], v[168:171], v[86:89], v[16:19]
	v_mfma_f32_16x16x32_bf16 v[20:23], v[168:171], v[90:93], v[20:23]
	v_mfma_f32_16x16x32_bf16 v[24:27], v[168:171], v[112:115], v[24:27]
	v_mfma_f32_16x16x32_bf16 v[28:31], v[168:171], v[252:255], v[28:31]
	s_waitcnt lgkmcnt(1)
	v_mfma_f32_16x16x32_bf16 v[32:35], v[244:247], v[86:89], v[32:35]
	v_mfma_f32_16x16x32_bf16 v[36:39], v[244:247], v[90:93], v[36:39]
	v_mfma_f32_16x16x32_bf16 v[40:43], v[244:247], v[112:115], v[40:43]
	v_mfma_f32_16x16x32_bf16 v[44:47], v[244:247], v[252:255], v[44:47]
	s_waitcnt lgkmcnt(0)
	v_mfma_f32_16x16x32_bf16 v[48:51], v[248:251], v[86:89], v[48:51]
	v_mfma_f32_16x16x32_bf16 v[52:55], v[248:251], v[90:93], v[52:55]
	v_mfma_f32_16x16x32_bf16 v[56:59], v[248:251], v[112:115], v[56:59]
	v_mfma_f32_16x16x32_bf16 v[60:63], v[248:251], v[252:255], v[60:63]
	s_waitcnt vmcnt(0) lgkmcnt(0)
	s_barrier
	s_add_u32 s98, s98, 0x80
	s_addc_u32 s99, s99, 0
	s_add_u32 s100, s100, 0x80
	s_addc_u32 s101, s101, 0
	ds_read_b128 v[120:123], v239 offset:32768
	ds_read_b128 v[140:143], v241 offset:32768
	ds_read_b128 v[152:155], v241 offset:34816
	ds_read_b128 v[156:159], v241 offset:36864
	ds_read_b128 v[160:163], v241 offset:38912
	ds_read_b128 v[124:127], v239 offset:34816
	ds_read_b128 v[128:131], v239 offset:36864
	ds_read_b128 v[132:135], v239 offset:38912
	s_waitcnt lgkmcnt(6)
	v_mfma_f32_16x16x32_bf16 v[0:3], v[120:123], v[140:143], v[0:3]
	ds_read_b128 v[164:167], v240 offset:32768
	s_waitcnt lgkmcnt(6)
	v_mfma_f32_16x16x32_bf16 v[4:7], v[120:123], v[152:155], v[4:7]
	ds_read_b128 v[86:89], v242 offset:32768
	s_waitcnt lgkmcnt(6)
	v_mfma_f32_16x16x32_bf16 v[8:11], v[120:123], v[156:159], v[8:11]
	ds_read_b128 v[90:93], v242 offset:34816
	s_waitcnt lgkmcnt(6)
	v_mfma_f32_16x16x32_bf16 v[12:15], v[120:123], v[160:163], v[12:15]
	ds_read_b128 v[112:115], v242 offset:36864
	s_waitcnt lgkmcnt(6)
	v_mfma_f32_16x16x32_bf16 v[16:19], v[124:127], v[140:143], v[16:19]
	ds_read_b128 v[252:255], v242 offset:38912
	v_mfma_f32_16x16x32_bf16 v[20:23], v[124:127], v[152:155], v[20:23]
	ds_read_b128 v[168:171], v240 offset:34816
	v_mfma_f32_16x16x32_bf16 v[24:27], v[124:127], v[156:159], v[24:27]
	ds_read_b128 v[244:247], v240 offset:36864
	v_mfma_f32_16x16x32_bf16 v[28:31], v[124:127], v[160:163], v[28:31]
	ds_read_b128 v[248:251], v240 offset:38912
	s_add_u32 m0, s5, 0x0
	s_waitcnt lgkmcnt(9)
	v_mfma_f32_16x16x32_bf16 v[32:35], v[128:131], v[140:143], v[32:35]
	global_load_lds_dwordx4 v66, s[98:99]
	s_add_u32 m0, s5, 0x1000
	v_mfma_f32_16x16x32_bf16 v[36:39], v[128:131], v[152:155], v[36:39]
	global_load_lds_dwordx4 v67, s[98:99]
	s_add_u32 m0, s5, 0x2000
	v_mfma_f32_16x16x32_bf16 v[40:43], v[128:131], v[156:159], v[40:43]
	global_load_lds_dwordx4 v68, s[98:99]
	s_add_u32 m0, s5, 0x3000
	v_mfma_f32_16x16x32_bf16 v[44:47], v[128:131], v[160:163], v[44:47]
	global_load_lds_dwordx4 v69, s[98:99]
	s_add_u32 m0, s5, 0x4000
	s_waitcnt lgkmcnt(8)
	v_mfma_f32_16x16x32_bf16 v[48:51], v[132:135], v[140:143], v[48:51]
	global_load_lds_dwordx4 v66, s[100:101]
	s_add_u32 m0, s5, 0x5000
	v_mfma_f32_16x16x32_bf16 v[52:55], v[132:135], v[152:155], v[52:55]
	global_load_lds_dwordx4 v67, s[100:101]
	s_add_u32 m0, s5, 0x6000
	v_mfma_f32_16x16x32_bf16 v[56:59], v[132:135], v[156:159], v[56:59]
	global_load_lds_dwordx4 v68, s[100:101]
	s_add_u32 m0, s5, 0x7000
	v_mfma_f32_16x16x32_bf16 v[60:63], v[132:135], v[160:163], v[60:63]
	global_load_lds_dwordx4 v69, s[100:101]
	s_waitcnt lgkmcnt(6)
	v_mfma_f32_16x16x32_bf16 v[0:3], v[164:167], v[86:89], v[0:3]
	s_waitcnt lgkmcnt(5)
	v_mfma_f32_16x16x32_bf16 v[4:7], v[164:167], v[90:93], v[4:7]
	s_waitcnt lgkmcnt(4)
	v_mfma_f32_16x16x32_bf16 v[8:11], v[164:167], v[112:115], v[8:11]
	s_waitcnt lgkmcnt(3)
	v_mfma_f32_16x16x32_bf16 v[12:15], v[164:167], v[252:255], v[12:15]
	s_waitcnt lgkmcnt(2)
	v_mfma_f32_16x16x32_bf16 v[16:19], v[168:171], v[86:89], v[16:19]
	v_mfma_f32_16x16x32_bf16 v[20:23], v[168:171], v[90:93], v[20:23]
	v_mfma_f32_16x16x32_bf16 v[24:27], v[168:171], v[112:115], v[24:27]
	v_mfma_f32_16x16x32_bf16 v[28:31], v[168:171], v[252:255], v[28:31]
	s_waitcnt lgkmcnt(1)
	v_mfma_f32_16x16x32_bf16 v[32:35], v[244:247], v[86:89], v[32:35]
	v_mfma_f32_16x16x32_bf16 v[36:39], v[244:247], v[90:93], v[36:39]
	v_mfma_f32_16x16x32_bf16 v[40:43], v[244:247], v[112:115], v[40:43]
	v_mfma_f32_16x16x32_bf16 v[44:47], v[244:247], v[252:255], v[44:47]
	s_waitcnt lgkmcnt(0)
	v_mfma_f32_16x16x32_bf16 v[48:51], v[248:251], v[86:89], v[48:51]
	v_mfma_f32_16x16x32_bf16 v[52:55], v[248:251], v[90:93], v[52:55]
	v_mfma_f32_16x16x32_bf16 v[56:59], v[248:251], v[112:115], v[56:59]
	v_mfma_f32_16x16x32_bf16 v[60:63], v[248:251], v[252:255], v[60:63]
	s_waitcnt vmcnt(0) lgkmcnt(0)
	s_barrier
	s_add_u32 s98, s98, 0x80
	s_addc_u32 s99, s99, 0
	s_add_u32 s100, s100, 0x80
	s_addc_u32 s101, s101, 0
	ds_read_b128 v[120:123], v239
	ds_read_b128 v[140:143], v241
	ds_read_b128 v[152:155], v241 offset:2048
	ds_read_b128 v[156:159], v241 offset:4096
	ds_read_b128 v[160:163], v241 offset:6144
	ds_read_b128 v[124:127], v239 offset:2048
	ds_read_b128 v[128:131], v239 offset:4096
	ds_read_b128 v[132:135], v239 offset:6144
	s_waitcnt lgkmcnt(6)
	v_mfma_f32_16x16x32_bf16 v[0:3], v[120:123], v[140:143], v[0:3]
	ds_read_b128 v[164:167], v240
	s_waitcnt lgkmcnt(6)
	v_mfma_f32_16x16x32_bf16 v[4:7], v[120:123], v[152:155], v[4:7]
	ds_read_b128 v[86:89], v242
	s_waitcnt lgkmcnt(6)
	v_mfma_f32_16x16x32_bf16 v[8:11], v[120:123], v[156:159], v[8:11]
	ds_read_b128 v[90:93], v242 offset:2048
	s_waitcnt lgkmcnt(6)
	v_mfma_f32_16x16x32_bf16 v[12:15], v[120:123], v[160:163], v[12:15]
	ds_read_b128 v[112:115], v242 offset:4096
	s_waitcnt lgkmcnt(6)
	v_mfma_f32_16x16x32_bf16 v[16:19], v[124:127], v[140:143], v[16:19]
	ds_read_b128 v[252:255], v242 offset:6144
	v_mfma_f32_16x16x32_bf16 v[20:23], v[124:127], v[152:155], v[20:23]
	ds_read_b128 v[168:171], v240 offset:2048
	v_mfma_f32_16x16x32_bf16 v[24:27], v[124:127], v[156:159], v[24:27]
	ds_read_b128 v[244:247], v240 offset:4096
	v_mfma_f32_16x16x32_bf16 v[28:31], v[124:127], v[160:163], v[28:31]
	ds_read_b128 v[248:251], v240 offset:6144
	s_add_u32 m0, s5, 0x8000
	s_waitcnt lgkmcnt(9)
	v_mfma_f32_16x16x32_bf16 v[32:35], v[128:131], v[140:143], v[32:35]
	global_load_lds_dwordx4 v66, s[98:99]
	s_add_u32 m0, s5, 0x9000
	v_mfma_f32_16x16x32_bf16 v[36:39], v[128:131], v[152:155], v[36:39]
	global_load_lds_dwordx4 v67, s[98:99]
	s_add_u32 m0, s5, 0xa000
	v_mfma_f32_16x16x32_bf16 v[40:43], v[128:131], v[156:159], v[40:43]
	global_load_lds_dwordx4 v68, s[98:99]
	s_add_u32 m0, s5, 0xb000
	v_mfma_f32_16x16x32_bf16 v[44:47], v[128:131], v[160:163], v[44:47]
	global_load_lds_dwordx4 v69, s[98:99]
	s_add_u32 m0, s5, 0xc000
	s_waitcnt lgkmcnt(8)
	v_mfma_f32_16x16x32_bf16 v[48:51], v[132:135], v[140:143], v[48:51]
	global_load_lds_dwordx4 v66, s[100:101]
	s_add_u32 m0, s5, 0xd000
	v_mfma_f32_16x16x32_bf16 v[52:55], v[132:135], v[152:155], v[52:55]
	global_load_lds_dwordx4 v67, s[100:101]
	s_add_u32 m0, s5, 0xe000
	v_mfma_f32_16x16x32_bf16 v[56:59], v[132:135], v[156:159], v[56:59]
	global_load_lds_dwordx4 v68, s[100:101]
	s_add_u32 m0, s5, 0xf000
	v_mfma_f32_16x16x32_bf16 v[60:63], v[132:135], v[160:163], v[60:63]
	global_load_lds_dwordx4 v69, s[100:101]
	s_waitcnt lgkmcnt(6)
	v_mfma_f32_16x16x32_bf16 v[0:3], v[164:167], v[86:89], v[0:3]
	s_waitcnt lgkmcnt(5)
	v_mfma_f32_16x16x32_bf16 v[4:7], v[164:167], v[90:93], v[4:7]
	s_waitcnt lgkmcnt(4)
	v_mfma_f32_16x16x32_bf16 v[8:11], v[164:167], v[112:115], v[8:11]
	s_waitcnt lgkmcnt(3)
	v_mfma_f32_16x16x32_bf16 v[12:15], v[164:167], v[252:255], v[12:15]
	s_waitcnt lgkmcnt(2)
	v_mfma_f32_16x16x32_bf16 v[16:19], v[168:171], v[86:89], v[16:19]
	v_mfma_f32_16x16x32_bf16 v[20:23], v[168:171], v[90:93], v[20:23]
	v_mfma_f32_16x16x32_bf16 v[24:27], v[168:171], v[112:115], v[24:27]
	v_mfma_f32_16x16x32_bf16 v[28:31], v[168:171], v[252:255], v[28:31]
	s_waitcnt lgkmcnt(1)
	v_mfma_f32_16x16x32_bf16 v[32:35], v[244:247], v[86:89], v[32:35]
	v_mfma_f32_16x16x32_bf16 v[36:39], v[244:247], v[90:93], v[36:39]
	v_mfma_f32_16x16x32_bf16 v[40:43], v[244:247], v[112:115], v[40:43]
	v_mfma_f32_16x16x32_bf16 v[44:47], v[244:247], v[252:255], v[44:47]
	s_waitcnt lgkmcnt(0)
	v_mfma_f32_16x16x32_bf16 v[48:51], v[248:251], v[86:89], v[48:51]
	v_mfma_f32_16x16x32_bf16 v[52:55], v[248:251], v[90:93], v[52:55]
	v_mfma_f32_16x16x32_bf16 v[56:59], v[248:251], v[112:115], v[56:59]
	v_mfma_f32_16x16x32_bf16 v[60:63], v[248:251], v[252:255], v[60:63]
	s_waitcnt vmcnt(0) lgkmcnt(0)
	s_barrier
	s_add_u32 s98, s98, 0x80
	s_addc_u32 s99, s99, 0
	s_add_u32 s100, s100, 0x80
	s_addc_u32 s101, s101, 0
	ds_read_b128 v[120:123], v239 offset:32768
	ds_read_b128 v[140:143], v241 offset:32768
	ds_read_b128 v[152:155], v241 offset:34816
	ds_read_b128 v[156:159], v241 offset:36864
	ds_read_b128 v[160:163], v241 offset:38912
	ds_read_b128 v[124:127], v239 offset:34816
	ds_read_b128 v[128:131], v239 offset:36864
	ds_read_b128 v[132:135], v239 offset:38912
	s_waitcnt lgkmcnt(6)
	v_mfma_f32_16x16x32_bf16 v[0:3], v[120:123], v[140:143], v[0:3]
	ds_read_b128 v[164:167], v240 offset:32768
	s_waitcnt lgkmcnt(6)
	v_mfma_f32_16x16x32_bf16 v[4:7], v[120:123], v[152:155], v[4:7]
	ds_read_b128 v[86:89], v242 offset:32768
	s_waitcnt lgkmcnt(6)
	v_mfma_f32_16x16x32_bf16 v[8:11], v[120:123], v[156:159], v[8:11]
	ds_read_b128 v[90:93], v242 offset:34816
	s_waitcnt lgkmcnt(6)
	v_mfma_f32_16x16x32_bf16 v[12:15], v[120:123], v[160:163], v[12:15]
	ds_read_b128 v[112:115], v242 offset:36864
	s_waitcnt lgkmcnt(6)
	v_mfma_f32_16x16x32_bf16 v[16:19], v[124:127], v[140:143], v[16:19]
	ds_read_b128 v[252:255], v242 offset:38912
	v_mfma_f32_16x16x32_bf16 v[20:23], v[124:127], v[152:155], v[20:23]
	ds_read_b128 v[168:171], v240 offset:34816
	v_mfma_f32_16x16x32_bf16 v[24:27], v[124:127], v[156:159], v[24:27]
	ds_read_b128 v[244:247], v240 offset:36864
	v_mfma_f32_16x16x32_bf16 v[28:31], v[124:127], v[160:163], v[28:31]
	ds_read_b128 v[248:251], v240 offset:38912
	s_add_u32 m0, s5, 0x0
	s_waitcnt lgkmcnt(9)
	v_mfma_f32_16x16x32_bf16 v[32:35], v[128:131], v[140:143], v[32:35]
	global_load_lds_dwordx4 v66, s[98:99]
	s_add_u32 m0, s5, 0x1000
	v_mfma_f32_16x16x32_bf16 v[36:39], v[128:131], v[152:155], v[36:39]
	global_load_lds_dwordx4 v67, s[98:99]
	s_add_u32 m0, s5, 0x2000
	v_mfma_f32_16x16x32_bf16 v[40:43], v[128:131], v[156:159], v[40:43]
	global_load_lds_dwordx4 v68, s[98:99]
	s_add_u32 m0, s5, 0x3000
	v_mfma_f32_16x16x32_bf16 v[44:47], v[128:131], v[160:163], v[44:47]
	global_load_lds_dwordx4 v69, s[98:99]
	s_add_u32 m0, s5, 0x4000
	s_waitcnt lgkmcnt(8)
	v_mfma_f32_16x16x32_bf16 v[48:51], v[132:135], v[140:143], v[48:51]
	global_load_lds_dwordx4 v66, s[100:101]
	s_add_u32 m0, s5, 0x5000
	v_mfma_f32_16x16x32_bf16 v[52:55], v[132:135], v[152:155], v[52:55]
	global_load_lds_dwordx4 v67, s[100:101]
	s_add_u32 m0, s5, 0x6000
	v_mfma_f32_16x16x32_bf16 v[56:59], v[132:135], v[156:159], v[56:59]
	global_load_lds_dwordx4 v68, s[100:101]
	s_add_u32 m0, s5, 0x7000
	v_mfma_f32_16x16x32_bf16 v[60:63], v[132:135], v[160:163], v[60:63]
	global_load_lds_dwordx4 v69, s[100:101]
	s_waitcnt lgkmcnt(6)
	v_mfma_f32_16x16x32_bf16 v[0:3], v[164:167], v[86:89], v[0:3]
	s_waitcnt lgkmcnt(5)
	v_mfma_f32_16x16x32_bf16 v[4:7], v[164:167], v[90:93], v[4:7]
	s_waitcnt lgkmcnt(4)
	v_mfma_f32_16x16x32_bf16 v[8:11], v[164:167], v[112:115], v[8:11]
	s_waitcnt lgkmcnt(3)
	v_mfma_f32_16x16x32_bf16 v[12:15], v[164:167], v[252:255], v[12:15]
	s_waitcnt lgkmcnt(2)
	v_mfma_f32_16x16x32_bf16 v[16:19], v[168:171], v[86:89], v[16:19]
	v_mfma_f32_16x16x32_bf16 v[20:23], v[168:171], v[90:93], v[20:23]
	v_mfma_f32_16x16x32_bf16 v[24:27], v[168:171], v[112:115], v[24:27]
	v_mfma_f32_16x16x32_bf16 v[28:31], v[168:171], v[252:255], v[28:31]
	s_waitcnt lgkmcnt(1)
	v_mfma_f32_16x16x32_bf16 v[32:35], v[244:247], v[86:89], v[32:35]
	v_mfma_f32_16x16x32_bf16 v[36:39], v[244:247], v[90:93], v[36:39]
	v_mfma_f32_16x16x32_bf16 v[40:43], v[244:247], v[112:115], v[40:43]
	v_mfma_f32_16x16x32_bf16 v[44:47], v[244:247], v[252:255], v[44:47]
	s_waitcnt lgkmcnt(0)
	v_mfma_f32_16x16x32_bf16 v[48:51], v[248:251], v[86:89], v[48:51]
	v_mfma_f32_16x16x32_bf16 v[52:55], v[248:251], v[90:93], v[52:55]
	v_mfma_f32_16x16x32_bf16 v[56:59], v[248:251], v[112:115], v[56:59]
	v_mfma_f32_16x16x32_bf16 v[60:63], v[248:251], v[252:255], v[60:63]
	s_waitcnt vmcnt(0) lgkmcnt(0)
	s_barrier
	s_add_u32 s98, s98, 0x80
	s_addc_u32 s99, s99, 0
	s_add_u32 s100, s100, 0x80
	s_addc_u32 s101, s101, 0
	ds_read_b128 v[120:123], v239
	ds_read_b128 v[140:143], v241
	ds_read_b128 v[152:155], v241 offset:2048
	ds_read_b128 v[156:159], v241 offset:4096
	ds_read_b128 v[160:163], v241 offset:6144
	ds_read_b128 v[124:127], v239 offset:2048
	ds_read_b128 v[128:131], v239 offset:4096
	ds_read_b128 v[132:135], v239 offset:6144
	s_waitcnt lgkmcnt(6)
	v_mfma_f32_16x16x32_bf16 v[0:3], v[120:123], v[140:143], v[0:3]
	ds_read_b128 v[164:167], v240
	s_waitcnt lgkmcnt(6)
	v_mfma_f32_16x16x32_bf16 v[4:7], v[120:123], v[152:155], v[4:7]
	ds_read_b128 v[86:89], v242
	s_waitcnt lgkmcnt(6)
	v_mfma_f32_16x16x32_bf16 v[8:11], v[120:123], v[156:159], v[8:11]
	ds_read_b128 v[90:93], v242 offset:2048
	s_waitcnt lgkmcnt(6)
	v_mfma_f32_16x16x32_bf16 v[12:15], v[120:123], v[160:163], v[12:15]
	ds_read_b128 v[112:115], v242 offset:4096
	s_waitcnt lgkmcnt(6)
	v_mfma_f32_16x16x32_bf16 v[16:19], v[124:127], v[140:143], v[16:19]
	ds_read_b128 v[252:255], v242 offset:6144
	v_mfma_f32_16x16x32_bf16 v[20:23], v[124:127], v[152:155], v[20:23]
	ds_read_b128 v[168:171], v240 offset:2048
	v_mfma_f32_16x16x32_bf16 v[24:27], v[124:127], v[156:159], v[24:27]
	ds_read_b128 v[244:247], v240 offset:4096
	v_mfma_f32_16x16x32_bf16 v[28:31], v[124:127], v[160:163], v[28:31]
	ds_read_b128 v[248:251], v240 offset:6144
	s_add_u32 m0, s5, 0x8000
	s_waitcnt lgkmcnt(9)
	v_mfma_f32_16x16x32_bf16 v[32:35], v[128:131], v[140:143], v[32:35]
	global_load_lds_dwordx4 v66, s[98:99]
	s_add_u32 m0, s5, 0x9000
	v_mfma_f32_16x16x32_bf16 v[36:39], v[128:131], v[152:155], v[36:39]
	global_load_lds_dwordx4 v67, s[98:99]
	s_add_u32 m0, s5, 0xa000
	v_mfma_f32_16x16x32_bf16 v[40:43], v[128:131], v[156:159], v[40:43]
	global_load_lds_dwordx4 v68, s[98:99]
	s_add_u32 m0, s5, 0xb000
	v_mfma_f32_16x16x32_bf16 v[44:47], v[128:131], v[160:163], v[44:47]
	global_load_lds_dwordx4 v69, s[98:99]
	s_add_u32 m0, s5, 0xc000
	s_waitcnt lgkmcnt(8)
	v_mfma_f32_16x16x32_bf16 v[48:51], v[132:135], v[140:143], v[48:51]
	global_load_lds_dwordx4 v66, s[100:101]
	s_add_u32 m0, s5, 0xd000
	v_mfma_f32_16x16x32_bf16 v[52:55], v[132:135], v[152:155], v[52:55]
	global_load_lds_dwordx4 v67, s[100:101]
	s_add_u32 m0, s5, 0xe000
	v_mfma_f32_16x16x32_bf16 v[56:59], v[132:135], v[156:159], v[56:59]
	global_load_lds_dwordx4 v68, s[100:101]
	s_add_u32 m0, s5, 0xf000
	v_mfma_f32_16x16x32_bf16 v[60:63], v[132:135], v[160:163], v[60:63]
	global_load_lds_dwordx4 v69, s[100:101]
	s_waitcnt lgkmcnt(6)
	v_mfma_f32_16x16x32_bf16 v[0:3], v[164:167], v[86:89], v[0:3]
	s_waitcnt lgkmcnt(5)
	v_mfma_f32_16x16x32_bf16 v[4:7], v[164:167], v[90:93], v[4:7]
	s_waitcnt lgkmcnt(4)
	v_mfma_f32_16x16x32_bf16 v[8:11], v[164:167], v[112:115], v[8:11]
	s_waitcnt lgkmcnt(3)
	v_mfma_f32_16x16x32_bf16 v[12:15], v[164:167], v[252:255], v[12:15]
	s_waitcnt lgkmcnt(2)
	v_mfma_f32_16x16x32_bf16 v[16:19], v[168:171], v[86:89], v[16:19]
	v_mfma_f32_16x16x32_bf16 v[20:23], v[168:171], v[90:93], v[20:23]
	v_mfma_f32_16x16x32_bf16 v[24:27], v[168:171], v[112:115], v[24:27]
	v_mfma_f32_16x16x32_bf16 v[28:31], v[168:171], v[252:255], v[28:31]
	s_waitcnt lgkmcnt(1)
	v_mfma_f32_16x16x32_bf16 v[32:35], v[244:247], v[86:89], v[32:35]
	v_mfma_f32_16x16x32_bf16 v[36:39], v[244:247], v[90:93], v[36:39]
	v_mfma_f32_16x16x32_bf16 v[40:43], v[244:247], v[112:115], v[40:43]
	v_mfma_f32_16x16x32_bf16 v[44:47], v[244:247], v[252:255], v[44:47]
	s_waitcnt lgkmcnt(0)
	v_mfma_f32_16x16x32_bf16 v[48:51], v[248:251], v[86:89], v[48:51]
	v_mfma_f32_16x16x32_bf16 v[52:55], v[248:251], v[90:93], v[52:55]
	v_mfma_f32_16x16x32_bf16 v[56:59], v[248:251], v[112:115], v[56:59]
	v_mfma_f32_16x16x32_bf16 v[60:63], v[248:251], v[252:255], v[60:63]
	s_waitcnt vmcnt(0) lgkmcnt(0)
	s_barrier
	ds_read_b128 v[120:123], v239 offset:32768
	ds_read_b128 v[140:143], v241 offset:32768
	ds_read_b128 v[152:155], v241 offset:34816
	ds_read_b128 v[156:159], v241 offset:36864
	ds_read_b128 v[160:163], v241 offset:38912
	ds_read_b128 v[124:127], v239 offset:34816
	ds_read_b128 v[128:131], v239 offset:36864
	ds_read_b128 v[132:135], v239 offset:38912
	s_waitcnt lgkmcnt(6)
	v_mfma_f32_16x16x32_bf16 v[0:3], v[120:123], v[140:143], v[0:3]
	ds_read_b128 v[164:167], v240 offset:32768
	s_waitcnt lgkmcnt(6)
	v_mfma_f32_16x16x32_bf16 v[4:7], v[120:123], v[152:155], v[4:7]
	ds_read_b128 v[86:89], v242 offset:32768
	s_waitcnt lgkmcnt(6)
	v_mfma_f32_16x16x32_bf16 v[8:11], v[120:123], v[156:159], v[8:11]
	ds_read_b128 v[90:93], v242 offset:34816
	s_waitcnt lgkmcnt(6)
	v_mfma_f32_16x16x32_bf16 v[12:15], v[120:123], v[160:163], v[12:15]
	ds_read_b128 v[112:115], v242 offset:36864
	s_waitcnt lgkmcnt(6)
	v_mfma_f32_16x16x32_bf16 v[16:19], v[124:127], v[140:143], v[16:19]
	ds_read_b128 v[252:255], v242 offset:38912
	v_mfma_f32_16x16x32_bf16 v[20:23], v[124:127], v[152:155], v[20:23]
	ds_read_b128 v[168:171], v240 offset:34816
	v_mfma_f32_16x16x32_bf16 v[24:27], v[124:127], v[156:159], v[24:27]
	ds_read_b128 v[244:247], v240 offset:36864
	v_mfma_f32_16x16x32_bf16 v[28:31], v[124:127], v[160:163], v[28:31]
	ds_read_b128 v[248:251], v240 offset:38912
	s_waitcnt lgkmcnt(9)
	v_mfma_f32_16x16x32_bf16 v[32:35], v[128:131], v[140:143], v[32:35]
	v_mfma_f32_16x16x32_bf16 v[36:39], v[128:131], v[152:155], v[36:39]
	v_mfma_f32_16x16x32_bf16 v[40:43], v[128:131], v[156:159], v[40:43]
	v_mfma_f32_16x16x32_bf16 v[44:47], v[128:131], v[160:163], v[44:47]
	s_waitcnt lgkmcnt(8)
	v_mfma_f32_16x16x32_bf16 v[48:51], v[132:135], v[140:143], v[48:51]
	v_mfma_f32_16x16x32_bf16 v[52:55], v[132:135], v[152:155], v[52:55]
	v_mfma_f32_16x16x32_bf16 v[56:59], v[132:135], v[156:159], v[56:59]
	v_mfma_f32_16x16x32_bf16 v[60:63], v[132:135], v[160:163], v[60:63]
	s_waitcnt lgkmcnt(6)
	v_mfma_f32_16x16x32_bf16 v[0:3], v[164:167], v[86:89], v[0:3]
	s_waitcnt lgkmcnt(5)
	v_mfma_f32_16x16x32_bf16 v[4:7], v[164:167], v[90:93], v[4:7]
	s_waitcnt lgkmcnt(4)
	v_mfma_f32_16x16x32_bf16 v[8:11], v[164:167], v[112:115], v[8:11]
	s_waitcnt lgkmcnt(3)
	v_mfma_f32_16x16x32_bf16 v[12:15], v[164:167], v[252:255], v[12:15]
	s_waitcnt lgkmcnt(2)
	v_mfma_f32_16x16x32_bf16 v[16:19], v[168:171], v[86:89], v[16:19]
	v_mfma_f32_16x16x32_bf16 v[20:23], v[168:171], v[90:93], v[20:23]
	v_mfma_f32_16x16x32_bf16 v[24:27], v[168:171], v[112:115], v[24:27]
	v_mfma_f32_16x16x32_bf16 v[28:31], v[168:171], v[252:255], v[28:31]
	s_waitcnt lgkmcnt(1)
	v_mfma_f32_16x16x32_bf16 v[32:35], v[244:247], v[86:89], v[32:35]
	v_mfma_f32_16x16x32_bf16 v[36:39], v[244:247], v[90:93], v[36:39]
	v_mfma_f32_16x16x32_bf16 v[40:43], v[244:247], v[112:115], v[40:43]
	v_mfma_f32_16x16x32_bf16 v[44:47], v[244:247], v[252:255], v[44:47]
	s_waitcnt lgkmcnt(0)
	v_mfma_f32_16x16x32_bf16 v[48:51], v[248:251], v[86:89], v[48:51]
	v_mfma_f32_16x16x32_bf16 v[52:55], v[248:251], v[90:93], v[52:55]
	v_mfma_f32_16x16x32_bf16 v[56:59], v[248:251], v[112:115], v[56:59]
	v_mfma_f32_16x16x32_bf16 v[60:63], v[248:251], v[252:255], v[60:63]
	s_waitcnt vmcnt(0) lgkmcnt(0)
	s_barrier
	s_nop 15
	ds_write_b32 v243, v0
	ds_write_b32 v243, v1 offset:528
	ds_write_b32 v243, v2 offset:1056
	ds_write_b32 v243, v3 offset:1584
	ds_write_b32 v243, v4 offset:64
	ds_write_b32 v243, v5 offset:592
	ds_write_b32 v243, v6 offset:1120
	ds_write_b32 v243, v7 offset:1648
	ds_write_b32 v243, v8 offset:128
	ds_write_b32 v243, v9 offset:656
	ds_write_b32 v243, v10 offset:1184
	ds_write_b32 v243, v11 offset:1712
	ds_write_b32 v243, v12 offset:192
	ds_write_b32 v243, v13 offset:720
	ds_write_b32 v243, v14 offset:1248
	ds_write_b32 v243, v15 offset:1776
	ds_write_b32 v243, v16 offset:8448
	ds_write_b32 v243, v17 offset:8976
	ds_write_b32 v243, v18 offset:9504
	ds_write_b32 v243, v19 offset:10032
	ds_write_b32 v243, v20 offset:8512
	ds_write_b32 v243, v21 offset:9040
	ds_write_b32 v243, v22 offset:9568
	ds_write_b32 v243, v23 offset:10096
	ds_write_b32 v243, v24 offset:8576
	ds_write_b32 v243, v25 offset:9104
	ds_write_b32 v243, v26 offset:9632
	ds_write_b32 v243, v27 offset:10160
	ds_write_b32 v243, v28 offset:8640
	ds_write_b32 v243, v29 offset:9168
	ds_write_b32 v243, v30 offset:9696
	ds_write_b32 v243, v31 offset:10224
	ds_write_b32 v243, v32 offset:16896
	ds_write_b32 v243, v33 offset:17424
	ds_write_b32 v243, v34 offset:17952
	ds_write_b32 v243, v35 offset:18480
	ds_write_b32 v243, v36 offset:16960
	ds_write_b32 v243, v37 offset:17488
	ds_write_b32 v243, v38 offset:18016
	ds_write_b32 v243, v39 offset:18544
	ds_write_b32 v243, v40 offset:17024
	ds_write_b32 v243, v41 offset:17552
	ds_write_b32 v243, v42 offset:18080
	ds_write_b32 v243, v43 offset:18608
	ds_write_b32 v243, v44 offset:17088
	ds_write_b32 v243, v45 offset:17616
	ds_write_b32 v243, v46 offset:18144
	ds_write_b32 v243, v47 offset:18672
	ds_write_b32 v243, v48 offset:25344
	ds_write_b32 v243, v49 offset:25872
	ds_write_b32 v243, v50 offset:26400
	ds_write_b32 v243, v51 offset:26928
	ds_write_b32 v243, v52 offset:25408
	ds_write_b32 v243, v53 offset:25936
	ds_write_b32 v243, v54 offset:26464
	ds_write_b32 v243, v55 offset:26992
	ds_write_b32 v243, v56 offset:25472
	ds_write_b32 v243, v57 offset:26000
	ds_write_b32 v243, v58 offset:26528
	ds_write_b32 v243, v59 offset:27056
	ds_write_b32 v243, v60 offset:25536
	ds_write_b32 v243, v61 offset:26064
	ds_write_b32 v243, v62 offset:26592
	ds_write_b32 v243, v63 offset:27120
	v_or_b32_e32 v0, s4, v78
	v_ashrrev_i32_e32 v1, 31, v0
	s_movk_i32 s4, 0x1ff
	v_cmp_lt_i32_e64 s[4:5], s4, v0
	v_lshl_add_u64 v[4:5], v[0:1], 1, s[12:13]
	v_lshl_add_u64 v[6:7], v[0:1], 2, s[38:39]
	v_or_b32_e32 v18, s6, v79
	v_or_b32_e32 v19, s6, v81
	v_or_b32_e32 v20, s6, v83
	v_or_b32_e32 v21, s6, v147
	v_mov_b32_e32 v22, v85
	v_mov_b32_e32 v23, v84
	v_mov_b32_e32 v24, v82
	v_mov_b32_e32 v25, v80
	s_waitcnt lgkmcnt(0)
	s_barrier
	s_branch .LBB0_179
